# k up-projection GEMM epilogue: head-norm gain vectors loaded once per tile instead of per (row group, column group); dataflow-checked removal of the vmcnt waits that only guarded those loads
# speedup vs baseline: 1.1344x; 1.0031x over previous
.LBB0_614:
	v_mov_b32_e32 v162, v0
	s_waitcnt vmcnt(7)
	v_mov_b32_e32 v6, v0
	s_waitcnt lgkmcnt(0)
	s_barrier
	s_nop 0
	v_and_b32_e32 v7, 14, v6
	v_ashrrev_i32_e32 v8, 1, v6
	v_and_or_b32 v7, v8, s51, v7
	s_waitcnt vmcnt(3)
	v_ashrrev_i32_e32 v23, 1, v7
	v_lshlrev_b32_e32 v7, 3, v6
	v_and_b32_e32 v24, 8, v7
	v_lshrrev_b32_e32 v7, 1, v6
	v_and_b32_e32 v7, 0x67, v7
	v_bfe_u32 v22, v6, 4, 2
	v_bfe_u32 v6, v6, 1, 3
	v_lshlrev_b32_e32 v8, 8, v7
	v_or_b32_e32 v9, 8, v7
	v_bitop3_b32 v7, v7, 15, 8 bitop3:0xc8
	v_or_b32_e32 v25, 8, v23
	v_bitop3_b32 v6, v24, v6, v22 bitop3:0x36
	v_bitop3_b32 v7, v24, v7, v22 bitop3:0x36
	v_or_b32_e32 v22, v24, v22
	v_bitop3_b32 v24, v23, v22, 7 bitop3:0x6c
	v_bitop3_b32 v22, v25, v22, 15 bitop3:0x6c
	v_lshlrev_b32_e32 v9, 8, v9
	v_lshlrev_b32_e32 v22, 4, v22
	v_lshl_or_b32 v14, v6, 4, v8
	v_lshl_or_b32 v15, v7, 4, v9
	v_lshlrev_b32_e32 v24, 4, v24
	v_lshl_or_b32 v22, v25, 8, v22
	v_or_b32_e32 v6, 0x18000, v14
	v_or_b32_e32 v10, 0x18000, v15
	v_or_b32_e32 v14, 0x19000, v14
	v_or_b32_e32 v18, 0x19000, v15
	v_lshl_or_b32 v23, v23, 8, v24
	v_add_u32_e32 v204, 0x10000, v22
	ds_read_b128 v[6:9], v6
	ds_read_b128 v[10:13], v10
	ds_read_b128 v[14:17], v14
	ds_read_b128 v[18:21], v18
	v_add_u32_e32 v167, 0x10000, v23
	ds_read_b128 v[22:25], v204
	s_waitcnt vmcnt(2)
	ds_read_b128 v[26:29], v167
	s_waitcnt vmcnt(1)
	ds_read_b128 v[30:33], v167 offset:4096
	s_setprio 1
	s_waitcnt lgkmcnt(1)
	v_mfma_f32_16x16x32_bf16 v[2:5], v[6:9], v[26:29], v[2:5]
	s_waitcnt vmcnt(0)
	v_mfma_f32_16x16x32_bf16 v[34:37], v[10:13], v[26:29], v[38:41]
	v_mfma_f32_16x16x32_bf16 v[38:41], v[14:17], v[26:29], v[42:45]
	v_mfma_f32_16x16x32_bf16 v[26:29], v[18:21], v[26:29], v[46:49]
	v_mfma_f32_16x16x32_bf16 v[42:45], v[6:9], v[22:25], v[50:53]
	v_mfma_f32_16x16x32_bf16 v[46:49], v[10:13], v[22:25], v[54:57]
	v_mfma_f32_16x16x32_bf16 v[50:53], v[14:17], v[22:25], v[58:61]
	s_nop 1
	ds_read_b128 v[54:57], v204 offset:4096
	ds_read_b128 v[58:61], v167 offset:8192
	v_mfma_f32_16x16x32_bf16 v[22:25], v[18:21], v[22:25], v[62:65]
	s_waitcnt lgkmcnt(2)
	v_mfma_f32_16x16x32_bf16 v[62:65], v[6:9], v[30:33], v[66:69]
	v_mfma_f32_16x16x32_bf16 v[66:69], v[10:13], v[30:33], v[70:73]
	v_mfma_f32_16x16x32_bf16 v[70:73], v[14:17], v[30:33], v[74:77]
	v_mfma_f32_16x16x32_bf16 v[30:33], v[18:21], v[30:33], v[78:81]
	s_waitcnt lgkmcnt(1)
	v_mfma_f32_16x16x32_bf16 v[74:77], v[6:9], v[54:57], v[82:85]
	s_waitcnt lgkmcnt(0)
	v_mfma_f32_16x16x32_bf16 v[176:179], v[6:9], v[58:61], v[98:101]
	v_mfma_f32_16x16x32_bf16 v[180:183], v[10:13], v[58:61], v[102:105]
	v_mfma_f32_16x16x32_bf16 v[184:187], v[14:17], v[58:61], v[106:109]
	v_mfma_f32_16x16x32_bf16 v[188:191], v[18:21], v[58:61], v[110:113]
	ds_read_b128 v[58:61], v204 offset:8192
	ds_read_b128 v[78:81], v167 offset:12288
	ds_read_b128 v[82:85], v204 offset:12288
	v_mfma_f32_16x16x32_bf16 v[168:171], v[10:13], v[54:57], v[86:89]
	v_mfma_f32_16x16x32_bf16 v[172:175], v[14:17], v[54:57], v[90:93]
	v_mfma_f32_16x16x32_bf16 v[54:57], v[18:21], v[54:57], v[94:97]
	s_waitcnt lgkmcnt(2)
	v_mfma_f32_16x16x32_bf16 v[192:195], v[6:9], v[58:61], v[114:117]
	v_mfma_f32_16x16x32_bf16 v[196:199], v[10:13], v[58:61], v[118:121]
	v_mfma_f32_16x16x32_bf16 v[200:203], v[14:17], v[58:61], v[122:125]
	v_mfma_f32_16x16x32_bf16 v[204:207], v[18:21], v[58:61], v[126:129]
	s_waitcnt lgkmcnt(1)
	v_mfma_f32_16x16x32_bf16 v[130:133], v[6:9], v[78:81], v[130:133]
	v_mfma_f32_16x16x32_bf16 v[134:137], v[10:13], v[78:81], v[134:137]
	s_waitcnt lgkmcnt(0)
	v_mfma_f32_16x16x32_bf16 v[6:9], v[6:9], v[82:85], v[146:149]
	v_mfma_f32_16x16x32_bf16 v[10:13], v[10:13], v[82:85], v[150:153]
	v_mfma_f32_16x16x32_bf16 v[138:141], v[14:17], v[78:81], v[138:141]
	v_mfma_f32_16x16x32_bf16 v[142:145], v[18:21], v[78:81], v[142:145]
	v_mfma_f32_16x16x32_bf16 v[146:149], v[14:17], v[82:85], v[154:157]
	v_mfma_f32_16x16x32_bf16 v[150:153], v[18:21], v[82:85], v[158:161]
	s_setprio 0
	v_mov_b32_e32 v14, v0
	s_nop 0
	v_and_b32_e32 v15, 14, v14
	v_ashrrev_i32_e32 v17, 1, v14
	v_and_or_b32 v15, v17, s51, v15
	v_lshlrev_b32_e32 v17, 3, v14
	v_bfe_u32 v16, v14, 4, 2
	v_and_b32_e32 v17, 8, v17
	v_ashrrev_i32_e32 v15, 1, v15
	v_or_b32_e32 v18, v17, v16
	v_bitop3_b32 v19, v15, v18, 7 bitop3:0x6c
	v_lshlrev_b32_e32 v20, 8, v15
	v_or_b32_e32 v15, 8, v15
	v_bitop3_b32 v18, v15, v18, 15 bitop3:0x6c
	v_lshlrev_b32_e32 v15, 8, v15
	v_lshl_or_b32 v18, v18, 4, v15
	v_lshrrev_b32_e32 v15, 1, v14
	v_and_b32_e32 v15, 0x67, v15
	v_bfe_u32 v14, v14, 1, 3
	v_lshl_or_b32 v19, v19, 4, v20
	v_bitop3_b32 v14, v17, v14, v16 bitop3:0x36
	v_lshlrev_b32_e32 v20, 8, v15
	v_lshl_or_b32 v20, v14, 4, v20
	v_or_b32_e32 v14, 8, v15
	v_bitop3_b32 v15, v15, 15, 8 bitop3:0xc8
	v_bitop3_b32 v15, v17, v15, v16 bitop3:0x36
	v_lshlrev_b32_e32 v14, 8, v14
	v_lshl_or_b32 v21, v15, 4, v14
	v_bitop3_b32 v14, v20, s52, v164 bitop3:0xde
	v_bitop3_b32 v58, v21, s52, v164 bitop3:0xde
	v_bitop3_b32 v20, v20, s53, v164 bitop3:0xde
	v_bitop3_b32 v21, v21, s53, v164 bitop3:0xde
	v_xad_u32 v212, v18, 64, v165
	ds_read_b128 v[14:17], v14
	ds_read_b128 v[154:157], v58
	ds_read_b128 v[158:161], v20
	ds_read_b128 v[208:211], v21
	v_xad_u32 v167, v19, 64, v165
	ds_read_b128 v[18:21], v212
	ds_read_b128 v[58:61], v167
	ds_read_b128 v[78:81], v167 offset:4096
	s_setprio 1
	s_waitcnt lgkmcnt(1)
	v_mfma_f32_16x16x32_bf16 v[126:129], v[14:17], v[58:61], v[2:5]
	v_mfma_f32_16x16x32_bf16 v[114:117], v[208:211], v[58:61], v[26:29]
	s_nop 1
	ds_read_b128 v[2:5], v212 offset:4096
	ds_read_b128 v[26:29], v167 offset:8192
	v_mfma_f32_16x16x32_bf16 v[122:125], v[154:157], v[58:61], v[34:37]
	v_mfma_f32_16x16x32_bf16 v[118:121], v[158:161], v[58:61], v[38:41]
	v_mfma_f32_16x16x32_bf16 v[110:113], v[14:17], v[18:21], v[42:45]
	v_mfma_f32_16x16x32_bf16 v[106:109], v[154:157], v[18:21], v[46:49]
	v_mfma_f32_16x16x32_bf16 v[102:105], v[158:161], v[18:21], v[50:53]
	v_mfma_f32_16x16x32_bf16 v[98:101], v[208:211], v[18:21], v[22:25]
	s_waitcnt lgkmcnt(2)
	v_mfma_f32_16x16x32_bf16 v[94:97], v[14:17], v[78:81], v[62:65]
	v_mfma_f32_16x16x32_bf16 v[90:93], v[154:157], v[78:81], v[66:69]
	v_mfma_f32_16x16x32_bf16 v[86:89], v[158:161], v[78:81], v[70:73]
	v_mfma_f32_16x16x32_bf16 v[82:85], v[208:211], v[78:81], v[30:33]
	s_waitcnt lgkmcnt(1)
	v_mfma_f32_16x16x32_bf16 v[78:81], v[14:17], v[2:5], v[74:77]
	v_mfma_f32_16x16x32_bf16 v[74:77], v[154:157], v[2:5], v[168:171]
	v_mfma_f32_16x16x32_bf16 v[70:73], v[158:161], v[2:5], v[172:175]
	v_mfma_f32_16x16x32_bf16 v[66:69], v[208:211], v[2:5], v[54:57]
	ds_read_b128 v[2:5], v212 offset:8192
	ds_read_b128 v[18:21], v167 offset:12288
	ds_read_b128 v[168:171], v212 offset:12288
	s_waitcnt lgkmcnt(3)
	v_mfma_f32_16x16x32_bf16 v[62:65], v[14:17], v[26:29], v[176:179]
	v_mfma_f32_16x16x32_bf16 v[58:61], v[154:157], v[26:29], v[180:183]
	v_mfma_f32_16x16x32_bf16 v[54:57], v[158:161], v[26:29], v[184:187]
	v_mfma_f32_16x16x32_bf16 v[50:53], v[208:211], v[26:29], v[188:191]
	s_waitcnt lgkmcnt(2)
	v_mfma_f32_16x16x32_bf16 v[46:49], v[14:17], v[2:5], v[192:195]
	v_mfma_f32_16x16x32_bf16 v[42:45], v[154:157], v[2:5], v[196:199]
	v_mfma_f32_16x16x32_bf16 v[38:41], v[158:161], v[2:5], v[200:203]
	v_mfma_f32_16x16x32_bf16 v[34:37], v[208:211], v[2:5], v[204:207]
	s_waitcnt lgkmcnt(1)
	v_mfma_f32_16x16x32_bf16 v[30:33], v[14:17], v[18:21], v[130:133]
	v_mfma_f32_16x16x32_bf16 v[26:29], v[154:157], v[18:21], v[134:137]
	v_mfma_f32_16x16x32_bf16 v[22:25], v[158:161], v[18:21], v[138:141]
	v_mfma_f32_16x16x32_bf16 v[18:21], v[208:211], v[18:21], v[142:145]
	s_waitcnt lgkmcnt(0)
	v_mfma_f32_16x16x32_bf16 v[14:17], v[14:17], v[168:171], v[6:9]
	v_mfma_f32_16x16x32_bf16 v[10:13], v[154:157], v[168:171], v[10:13]
	v_mfma_f32_16x16x32_bf16 v[6:9], v[158:161], v[168:171], v[146:149]
	v_mfma_f32_16x16x32_bf16 v[2:5], v[208:211], v[168:171], v[150:153]
	s_setprio 0
	s_cmp_ge_i32 s50, s46
	s_cselect_b64 s[28:29], -1, 0
	s_and_b64 vcc, exec, s[28:29]
	s_cbranch_vccnz .LBB0_616
	s_lshl_b32 s2, s43, 8
	s_ashr_i32 s3, s2, 31
	v_lshlrev_b32_e32 v130, 4, v162
	s_lshl_b64 s[2:3], s[2:3], 8
	v_and_b32_e32 v130, 0x70, v130
	v_lshlrev_b32_e32 v131, 5, v162
	s_add_u32 s2, s34, s2
	v_and_or_b32 v162, v131, s40, v130
	s_addc_u32 s3, s35, s3
	v_lshl_add_u64 v[138:139], s[2:3], 0, v[162:163]
	s_lshl_b32 s4, s38, 8
	v_add_co_u32_e32 v130, vcc, s44, v138
	s_ashr_i32 s5, s4, 31
	s_nop 0
	v_addc_co_u32_e32 v131, vcc, 0, v139, vcc
	s_lshl_b64 s[4:5], s[4:5], 8
	v_add_co_u32_e32 v134, vcc, s42, v138
	s_add_u32 s4, s37, s4
	s_nop 0
	v_addc_co_u32_e32 v135, vcc, 0, v139, vcc
	s_addc_u32 s5, s39, s5
	v_add_co_u32_e32 v146, vcc, s41, v138
	v_lshl_add_u64 v[154:155], s[4:5], 0, v[162:163]
	s_nop 0
	v_addc_co_u32_e32 v147, vcc, 0, v139, vcc
	v_add_co_u32_e32 v150, vcc, s44, v154
	global_load_dwordx4 v[130:133], v[130:131], off
	s_nop 0
	global_load_dwordx4 v[134:137], v[134:135], off
	v_addc_co_u32_e32 v151, vcc, 0, v155, vcc
	v_add_co_u32_e32 v156, vcc, s42, v154
	global_load_dwordx4 v[138:141], v162, s[2:3]
	global_load_dwordx4 v[142:145], v162, s[4:5]
	v_addc_co_u32_e32 v157, vcc, 0, v155, vcc
	v_add_co_u32_e32 v158, vcc, s41, v154
	global_load_dwordx4 v[146:149], v[146:147], off
	s_nop 0
	global_load_dwordx4 v[150:153], v[150:151], off
	v_addc_co_u32_e32 v159, vcc, 0, v155, vcc
	global_load_dwordx4 v[154:157], v[156:157], off
	s_nop 0
	global_load_dwordx4 v[158:161], v[158:159], off
	v_mov_b32_e32 v162, v0
	s_nop 0
	v_ashrrev_i32_e32 v167, 4, v162
	v_xor_b32_e32 v162, v167, v162
	v_lshlrev_b32_e32 v167, 8, v167
	v_lshlrev_b32_e32 v162, 4, v162
	v_and_or_b32 v162, v162, s45, v167
	s_waitcnt vmcnt(0)
	ds_write_b128 v162, v[138:141]
	ds_write_b128 v162, v[130:133] offset:8192
	ds_write_b128 v162, v[134:137] offset:16384
	ds_write_b128 v162, v[146:149] offset:24576
	ds_write_b128 v162, v[142:145] offset:32768
	ds_write_b128 v162, v[150:153] offset:40960
	ds_write_b128 v162, v[154:157] offset:49152
	ds_write_b128 v162, v[158:161] offset:57344

.LBB0_624:
	v_lshlrev_b32_e32 v162, 4, v149
	v_mov_b32_e32 v194, 0x0
	v_bfe_u32 v196, v0, 4, 2
	v_lshlrev_b32_e32 v196, 4, v196
	v_add_u32_e32 v194, v194, v196
	v_mov_b32_e32 v195, 0x100
	v_bfe_u32 v196, v0, 4, 2
	v_lshlrev_b32_e32 v196, 5, v196
	v_add_u32_e32 v195, v195, v196
	global_load_dwordx4 v[170:173], v194, s[20:21]
	global_load_dwordx4 v[174:177], v194, s[20:21] offset:64
	global_load_dwordx4 v[178:181], v194, s[20:21] offset:128
	global_load_dwordx4 v[182:185], v194, s[20:21] offset:192
	global_load_dwordx4 v[186:189], v195, s[20:21]
	global_load_dwordx4 v[190:193], v195, s[20:21] offset:16
	v_mul_f32_e32 v167, v127, v127
	v_fmac_f32_e32 v167, v126, v126
	v_fmac_f32_e32 v167, v128, v128
	v_fmac_f32_e32 v167, v129, v129
	v_fmac_f32_e32 v167, v122, v122
	v_fmac_f32_e32 v167, v123, v123
	v_fmac_f32_e32 v167, v124, v124
	v_fmac_f32_e32 v167, v125, v125
	v_fmac_f32_e32 v167, v118, v118
	v_fmac_f32_e32 v167, v119, v119
	v_fmac_f32_e32 v167, v120, v120
	v_fmac_f32_e32 v167, v121, v121
	v_fmac_f32_e32 v167, v114, v114
	v_fmac_f32_e32 v167, v115, v115
	v_fmac_f32_e32 v167, v116, v116
	s_waitcnt vmcnt(0)
	v_pk_mul_f32 v[140:141], v[130:131], v[130:131]
	v_fmac_f32_e32 v167, v117, v117
	v_add_f32_e32 v140, v167, v140
	v_pk_mul_f32 v[144:145], v[132:133], v[132:133]
	v_add_f32_e32 v140, v141, v140
	v_add_f32_e32 v140, v144, v140
	v_and_b32_e32 v146, 64, v166
	v_pk_mul_f32 v[156:157], v[134:135], v[134:135]
	v_add_f32_e32 v140, v145, v140
	v_xor_b32_e32 v143, 16, v166
	v_add_u32_e32 v168, 64, v146
	v_add_f32_e32 v140, v156, v140
	v_pk_mul_f32 v[158:159], v[136:137], v[136:137]
	v_cmp_lt_i32_e32 vcc, v143, v168
	v_add_f32_e32 v140, v157, v140
	v_add_f32_e32 v140, v158, v140
	v_cndmask_b32_e32 v143, v166, v143, vcc
	v_lshlrev_b32_e32 v146, 2, v143
	v_add_f32_e32 v140, v159, v140
	ds_bpermute_b32 v141, v146, v140
	v_xor_b32_e32 v148, 32, v166
	v_cmp_lt_i32_e32 vcc, v148, v168
	v_lshrrev_b32_e32 v151, 6, v150
	s_lshl_b32 s2, s58, 2
	v_cndmask_b32_e32 v144, v166, v148, vcc
	v_lshlrev_b32_e32 v148, 2, v144
	s_waitcnt lgkmcnt(0)
	v_add_f32_e32 v141, v140, v141
	ds_bpermute_b32 v156, v148, v141
	v_mov_b64_e32 v[160:161], s[24:25]
	v_and_or_b32 v140, v151, 3, s2
	v_mad_i64_i32 v[144:145], s[2:3], v139, s57, v[160:161]
	s_waitcnt lgkmcnt(0)
	v_add_f32_e32 v139, v141, v156
	v_fmamk_f32 v139, v139, 0x3c2aaaab, v1
	v_mul_f32_e32 v141, 0x4b800000, v139
	v_cmp_gt_f32_e32 vcc, s56, v139
	v_mul_lo_u32 v140, v140, s55
	v_mov_b32_e32 v143, v163
	v_cndmask_b32_e32 v139, v139, v141, vcc
	v_rsq_f32_e32 v139, v139
	v_ashrrev_i32_e32 v141, 31, v140
	v_lshl_add_u64 v[144:145], v[140:141], 1, v[144:145]
	v_lshl_add_u64 v[156:157], v[144:145], 0, v[142:143]
	v_mul_f32_e32 v143, 0x45800000, v139
	v_cndmask_b32_e32 v158, v139, v143, vcc
	v_mul_f32_e32 v126, v126, v158
	v_mul_f32_e32 v127, v127, v158
	v_mul_f32_e32 v128, v128, v158
	v_mul_f32_e32 v129, v129, v158
	v_mul_f32_e32 v122, v122, v158
	v_mul_f32_e32 v123, v123, v158
	v_mul_f32_e32 v124, v124, v158
	v_mul_f32_e32 v125, v125, v158
	v_mul_f32_e32 v118, v118, v158
	v_mul_f32_e32 v119, v119, v158
	v_mul_f32_e32 v120, v120, v158
	v_mul_f32_e32 v121, v121, v158
	v_mul_f32_e32 v114, v114, v158
	v_mul_f32_e32 v115, v115, v158
	v_mul_f32_e32 v116, v116, v158
	v_mul_f32_e32 v117, v117, v158
	s_cmp_eq_u32 s62, 1
	v_cmp_gt_u32_e64 s[4:5], 2, v149
	s_cselect_b64 s[30:31], -1, 0
	v_mul_f32_e32 v126, v170, v126
	v_mul_f32_e32 v127, v171, v127
	v_mul_f32_e32 v128, v172, v128
	v_mul_f32_e32 v129, v173, v129
	v_cvt_pk_bf16_f32 v126, v126, v127
	v_cvt_pk_bf16_f32 v127, v128, v129
	global_store_dwordx2 v[156:157], v[126:127], off
	s_cmp_lg_u32 s62, 1
	v_mul_f32_e32 v122, v174, v122
	v_mul_f32_e32 v123, v175, v123
	v_mul_f32_e32 v124, v176, v124
	v_mul_f32_e32 v125, v177, v125
	v_cvt_pk_bf16_f32 v122, v122, v123
	v_cvt_pk_bf16_f32 v123, v124, v125
	global_store_dwordx2 v[156:157], v[122:123], off offset:32
	v_mul_f32_e32 v118, v178, v118
	v_mul_f32_e32 v119, v179, v119
	v_mul_f32_e32 v120, v180, v120
	v_mul_f32_e32 v121, v121, v181
	v_cvt_pk_bf16_f32 v118, v118, v119
	v_cvt_pk_bf16_f32 v119, v120, v121
	global_store_dwordx2 v[156:157], v[118:119], off offset:64
	v_and_b32_e32 v122, 16, v150
	v_cmp_eq_u32_e64 s[2:3], 0, v122
	v_mul_f32_e32 v114, v114, v182
	v_mul_f32_e32 v115, v115, v183
	v_mul_f32_e32 v116, v116, v184
	v_mul_f32_e32 v117, v117, v185
	v_cvt_pk_bf16_f32 v114, v114, v115
	v_cvt_pk_bf16_f32 v115, v116, v117
	global_store_dwordx2 v[156:157], v[114:115], off offset:96
	s_nop 0
	v_mov_b32_e32 v114, v186
	v_mov_b32_e32 v115, v187
	v_mov_b32_e32 v116, v188
	v_mov_b32_e32 v117, v189
	v_pk_mul_f32 v[114:115], v[158:159], v[114:115] op_sel_hi:[0,1]
	v_pk_mul_f32 v[116:117], v[158:159], v[116:117] op_sel_hi:[0,1]
	v_pk_mul_f32 v[122:123], v[158:159], v[190:191] op_sel_hi:[0,1]
	v_pk_mul_f32 v[124:125], v[158:159], v[192:193] op_sel_hi:[0,1]
	v_pk_mul_f32 v[120:121], v[130:131], v[114:115]
	v_pk_mul_f32 v[118:119], v[132:133], v[116:117]
	v_pk_mul_f32 v[116:117], v[134:135], v[122:123]
	v_pk_mul_f32 v[114:115], v[136:137], v[124:125]
	s_cbranch_scc1 .LBB0_626
	v_add_u32_e32 v122, s60, v147
	v_ashrrev_i32_e32 v123, 6, v122
	v_and_b32_e32 v122, 63, v122
	v_cndmask_b32_e64 v122, v122, v123, s[4:5]
	v_cvt_f32_i32_e32 v130, v122
	ds_bpermute_b32 v122, v146, v120
	ds_bpermute_b32 v123, v146, v121
	v_mul_f32_e32 v125, 0x3ea1e89b, v130
	v_mul_f32_e32 v126, 0.15915494, v130
	v_mul_f32_e32 v127, 0.15915494, v125
	v_sin_f32_e32 v124, v126
	v_sin_f32_e32 v125, v127
	v_mul_f32_e32 v129, 0x3d0186e3, v130
	v_mul_f32_e32 v132, 0.15915494, v129
	v_cos_f32_e32 v126, v126
	s_waitcnt lgkmcnt(0)
	v_pk_mul_f32 v[122:123], v[124:125], v[122:123]
	v_mul_f32_e32 v125, 0x3dcccccd, v130
	ds_bpermute_b32 v124, v146, v118
	v_mul_f32_e32 v131, 0.15915494, v125
	ds_bpermute_b32 v125, v146, v119
	v_cos_f32_e32 v127, v127
	v_sin_f32_e32 v128, v131
	v_sin_f32_e32 v129, v132
	v_cndmask_b32_e64 v123, v123, -v123, s[2:3]
	v_cndmask_b32_e64 v122, v122, -v122, s[2:3]
	v_pk_fma_f32 v[120:121], v[126:127], v[120:121], v[122:123]
	s_waitcnt lgkmcnt(0)
	v_pk_mul_f32 v[124:125], v[128:129], v[124:125]
	v_mul_f32_e32 v127, 0x3c23d70b, v130
	v_mul_f32_e32 v129, 0x3b4f3e39, v130
	v_cos_f32_e32 v122, v131
	v_cos_f32_e32 v123, v132
	ds_bpermute_b32 v126, v146, v116
	v_mul_f32_e32 v131, 0.15915494, v127
	ds_bpermute_b32 v127, v146, v117
	v_mul_f32_e32 v132, 0.15915494, v129
	v_sin_f32_e32 v128, v131
	v_sin_f32_e32 v129, v132
	v_cndmask_b32_e64 v125, v125, -v125, s[2:3]
	v_cndmask_b32_e64 v124, v124, -v124, s[2:3]
	v_pk_fma_f32 v[118:119], v[122:123], v[118:119], v[124:125]
	v_cos_f32_e32 v122, v131
	v_cos_f32_e32 v123, v132
	s_waitcnt lgkmcnt(0)
	v_pk_mul_f32 v[124:125], v[128:129], v[126:127]
	v_mul_f32_e32 v127, 0x3a831270, v130
	v_mul_f32_e32 v129, 0x39a5cb61, v130
	ds_bpermute_b32 v126, v146, v114
	v_mul_f32_e32 v131, 0.15915494, v127
	ds_bpermute_b32 v127, v146, v115
	v_mul_f32_e32 v130, 0.15915494, v129
	v_sin_f32_e32 v128, v131
	v_sin_f32_e32 v129, v130
	v_cndmask_b32_e64 v125, v125, -v125, s[2:3]
	v_cndmask_b32_e64 v124, v124, -v124, s[2:3]
	v_pk_fma_f32 v[116:117], v[122:123], v[116:117], v[124:125]
	v_cos_f32_e32 v122, v131
	v_cos_f32_e32 v123, v130
	s_waitcnt lgkmcnt(0)
	v_pk_mul_f32 v[124:125], v[128:129], v[126:127]
	s_nop 0
	v_cndmask_b32_e64 v125, v125, -v125, s[2:3]
	v_cndmask_b32_e64 v124, v124, -v124, s[2:3]
	v_pk_fma_f32 v[114:115], v[122:123], v[114:115], v[124:125]

.LBB0_632:
	v_mul_f32_e32 v127, v111, v111
	v_fmac_f32_e32 v127, v110, v110
	v_fmac_f32_e32 v127, v112, v112
	v_fmac_f32_e32 v127, v113, v113
	v_fmac_f32_e32 v127, v106, v106
	v_fmac_f32_e32 v127, v107, v107
	v_fmac_f32_e32 v127, v108, v108
	v_fmac_f32_e32 v127, v109, v109
	v_fmac_f32_e32 v127, v102, v102
	v_fmac_f32_e32 v127, v103, v103
	v_fmac_f32_e32 v127, v104, v104
	v_fmac_f32_e32 v127, v105, v105
	v_fmac_f32_e32 v127, v98, v98
	v_fmac_f32_e32 v127, v99, v99
	v_fmac_f32_e32 v127, v100, v100
	s_waitcnt vmcnt(0)
	v_pk_mul_f32 v[136:137], v[114:115], v[114:115]
	v_fmac_f32_e32 v127, v101, v101
	v_add_f32_e32 v127, v127, v136
	v_pk_mul_f32 v[142:143], v[116:117], v[116:117]
	v_add_f32_e32 v127, v137, v127
	v_add_f32_e32 v127, v142, v127
	v_pk_mul_f32 v[144:145], v[118:119], v[118:119]
	v_add_f32_e32 v127, v143, v127
	v_add_f32_e32 v127, v144, v127
	v_pk_mul_f32 v[150:151], v[120:121], v[120:121]
	v_add_f32_e32 v127, v145, v127
	v_add_f32_e32 v127, v150, v127
	v_add_f32_e32 v127, v151, v127
	ds_bpermute_b32 v129, v146, v127
	v_mov_b64_e32 v[136:137], s[24:25]
	v_lshlrev_b32_e32 v126, 1, v126
	s_waitcnt lgkmcnt(0)
	v_add_f32_e32 v129, v127, v129
	ds_bpermute_b32 v131, v148, v129
	v_mov_b32_e32 v127, v163
	s_waitcnt lgkmcnt(0)
	v_add_f32_e32 v129, v129, v131
	v_fmamk_f32 v129, v129, 0x3c2aaaab, v1
	v_mul_f32_e32 v131, 0x4b800000, v129
	v_cmp_gt_f32_e32 vcc, s56, v129
	s_nop 1
	v_cndmask_b32_e32 v129, v129, v131, vcc
	v_rsq_f32_e32 v131, v129
	v_mad_i64_i32 v[128:129], s[6:7], v128, s57, v[136:137]
	v_lshl_add_u64 v[128:129], v[140:141], 1, v[128:129]
	v_lshl_add_u64 v[136:137], v[128:129], 0, v[126:127]
	v_mul_f32_e32 v127, 0x45800000, v131
	v_cndmask_b32_e32 v142, v131, v127, vcc
	v_mul_f32_e32 v110, v110, v142
	v_mul_f32_e32 v111, v111, v142
	v_mul_f32_e32 v112, v112, v142
	v_mul_f32_e32 v113, v113, v142
	v_mul_f32_e32 v106, v106, v142
	v_mul_f32_e32 v107, v107, v142
	v_mul_f32_e32 v108, v108, v142
	v_mul_f32_e32 v109, v109, v142
	v_mul_f32_e32 v102, v102, v142
	v_mul_f32_e32 v103, v103, v142
	v_mul_f32_e32 v104, v104, v142
	v_mul_f32_e32 v105, v105, v142
	v_mul_f32_e32 v98, v98, v142
	v_mul_f32_e32 v99, v99, v142
	v_mul_f32_e32 v100, v100, v142
	v_mul_f32_e32 v101, v101, v142
	s_andn2_b64 vcc, exec, s[30:31]
	v_mul_f32_e32 v110, v170, v110
	v_mul_f32_e32 v111, v171, v111
	v_mul_f32_e32 v112, v172, v112
	v_mul_f32_e32 v113, v173, v113
	v_cvt_pk_bf16_f32 v110, v110, v111
	v_cvt_pk_bf16_f32 v111, v112, v113
	global_store_dwordx2 v[136:137], v[110:111], off
	v_mul_f32_e32 v106, v174, v106
	v_mul_f32_e32 v107, v175, v107
	v_mul_f32_e32 v108, v176, v108
	v_mul_f32_e32 v109, v177, v109
	v_cvt_pk_bf16_f32 v106, v106, v107
	v_cvt_pk_bf16_f32 v107, v108, v109
	global_store_dwordx2 v[136:137], v[106:107], off offset:32
	v_mul_f32_e32 v102, v178, v102
	v_mul_f32_e32 v103, v179, v103
	v_mul_f32_e32 v104, v180, v104
	v_mul_f32_e32 v105, v105, v181
	v_cvt_pk_bf16_f32 v102, v102, v103
	v_cvt_pk_bf16_f32 v103, v104, v105
	global_store_dwordx2 v[136:137], v[102:103], off offset:64
	v_cndmask_b32_e64 v106, 0, 1, s[30:31]
	v_cmp_ne_u32_e64 s[6:7], 1, v106
	v_mul_f32_e32 v98, v98, v182
	v_mul_f32_e32 v99, v99, v183
	v_mul_f32_e32 v100, v100, v184
	v_mul_f32_e32 v101, v101, v185
	v_cvt_pk_bf16_f32 v98, v98, v99
	v_cvt_pk_bf16_f32 v99, v100, v101
	global_store_dwordx2 v[136:137], v[98:99], off offset:96
	s_nop 0
	v_mov_b32_e32 v98, v186
	v_mov_b32_e32 v99, v187
	v_mov_b32_e32 v100, v188
	v_mov_b32_e32 v101, v189
	v_pk_mul_f32 v[98:99], v[142:143], v[98:99] op_sel_hi:[0,1]
	v_pk_mul_f32 v[100:101], v[142:143], v[100:101] op_sel_hi:[0,1]
	v_pk_mul_f32 v[106:107], v[142:143], v[190:191] op_sel_hi:[0,1]
	v_pk_mul_f32 v[108:109], v[142:143], v[192:193] op_sel_hi:[0,1]
	v_pk_mul_f32 v[104:105], v[114:115], v[98:99]
	v_pk_mul_f32 v[102:103], v[116:117], v[100:101]
	v_pk_mul_f32 v[100:101], v[118:119], v[106:107]
	v_pk_mul_f32 v[98:99], v[120:121], v[108:109]
	s_cbranch_vccnz .LBB0_634
	v_add_u32_e32 v106, s60, v130
	v_ashrrev_i32_e32 v107, 6, v106
	v_and_b32_e32 v106, 63, v106
	v_cndmask_b32_e64 v106, v106, v107, s[4:5]
	v_cvt_f32_i32_e32 v114, v106
	ds_bpermute_b32 v106, v146, v104
	ds_bpermute_b32 v107, v146, v105
	v_mul_f32_e32 v109, 0x3ea1e89b, v114
	v_mul_f32_e32 v110, 0.15915494, v114
	v_mul_f32_e32 v111, 0.15915494, v109
	v_sin_f32_e32 v108, v110
	v_sin_f32_e32 v109, v111
	v_mul_f32_e32 v113, 0x3d0186e3, v114
	v_mul_f32_e32 v116, 0.15915494, v113
	v_cos_f32_e32 v110, v110
	s_waitcnt lgkmcnt(0)
	v_pk_mul_f32 v[106:107], v[108:109], v[106:107]
	v_mul_f32_e32 v109, 0x3dcccccd, v114
	ds_bpermute_b32 v108, v146, v102
	v_mul_f32_e32 v115, 0.15915494, v109
	ds_bpermute_b32 v109, v146, v103
	v_cos_f32_e32 v111, v111
	v_sin_f32_e32 v112, v115
	v_sin_f32_e32 v113, v116
	v_cndmask_b32_e64 v107, v107, -v107, s[2:3]
	v_cndmask_b32_e64 v106, v106, -v106, s[2:3]
	v_pk_fma_f32 v[104:105], v[110:111], v[104:105], v[106:107]
	s_waitcnt lgkmcnt(0)
	v_pk_mul_f32 v[108:109], v[112:113], v[108:109]
	v_mul_f32_e32 v111, 0x3c23d70b, v114
	v_mul_f32_e32 v113, 0x3b4f3e39, v114
	v_cos_f32_e32 v106, v115
	v_cos_f32_e32 v107, v116
	ds_bpermute_b32 v110, v146, v100
	v_mul_f32_e32 v115, 0.15915494, v111
	ds_bpermute_b32 v111, v146, v101
	v_mul_f32_e32 v116, 0.15915494, v113
	v_sin_f32_e32 v112, v115
	v_sin_f32_e32 v113, v116
	v_cndmask_b32_e64 v109, v109, -v109, s[2:3]
	v_cndmask_b32_e64 v108, v108, -v108, s[2:3]
	v_pk_fma_f32 v[102:103], v[106:107], v[102:103], v[108:109]
	v_cos_f32_e32 v106, v115
	v_cos_f32_e32 v107, v116
	s_waitcnt lgkmcnt(0)
	v_pk_mul_f32 v[108:109], v[112:113], v[110:111]
	v_mul_f32_e32 v111, 0x3a831270, v114
	v_mul_f32_e32 v113, 0x39a5cb61, v114
	ds_bpermute_b32 v110, v146, v98
	v_mul_f32_e32 v115, 0.15915494, v111
	ds_bpermute_b32 v111, v146, v99
	v_mul_f32_e32 v114, 0.15915494, v113
	v_sin_f32_e32 v112, v115
	v_sin_f32_e32 v113, v114
	v_cndmask_b32_e64 v109, v109, -v109, s[2:3]
	v_cndmask_b32_e64 v108, v108, -v108, s[2:3]
	v_pk_fma_f32 v[100:101], v[106:107], v[100:101], v[108:109]
	v_cos_f32_e32 v106, v115
	v_cos_f32_e32 v107, v114
	s_waitcnt lgkmcnt(0)
	v_pk_mul_f32 v[108:109], v[112:113], v[110:111]
	s_nop 0
	v_cndmask_b32_e64 v109, v109, -v109, s[2:3]
	v_cndmask_b32_e64 v108, v108, -v108, s[2:3]
	v_pk_fma_f32 v[98:99], v[106:107], v[98:99], v[108:109]

.LBB0_640:
	v_mul_f32_e32 v107, v95, v95
	v_fmac_f32_e32 v107, v94, v94
	v_fmac_f32_e32 v107, v96, v96
	v_fmac_f32_e32 v107, v97, v97
	v_fmac_f32_e32 v107, v90, v90
	v_fmac_f32_e32 v107, v91, v91
	v_fmac_f32_e32 v107, v92, v92
	v_fmac_f32_e32 v107, v93, v93
	v_fmac_f32_e32 v107, v86, v86
	v_fmac_f32_e32 v107, v87, v87
	v_fmac_f32_e32 v107, v88, v88
	v_fmac_f32_e32 v107, v89, v89
	v_fmac_f32_e32 v107, v82, v82
	v_fmac_f32_e32 v107, v83, v83
	v_fmac_f32_e32 v107, v84, v84
	s_waitcnt vmcnt(0)
	v_pk_mul_f32 v[114:115], v[98:99], v[98:99]
	v_fmac_f32_e32 v107, v85, v85
	v_add_f32_e32 v107, v107, v114
	v_pk_mul_f32 v[116:117], v[100:101], v[100:101]
	v_add_f32_e32 v107, v115, v107
	v_add_f32_e32 v107, v116, v107
	v_pk_mul_f32 v[118:119], v[102:103], v[102:103]
	v_add_f32_e32 v107, v117, v107
	v_add_f32_e32 v107, v118, v107
	v_pk_mul_f32 v[120:121], v[104:105], v[104:105]
	v_add_f32_e32 v107, v119, v107
	v_add_f32_e32 v107, v120, v107
	v_add_f32_e32 v107, v121, v107
	ds_bpermute_b32 v109, v146, v107
	v_mov_b64_e32 v[114:115], s[24:25]
	v_mov_b32_e32 v127, v163
	s_waitcnt lgkmcnt(0)
	v_add_f32_e32 v107, v107, v109
	ds_bpermute_b32 v109, v148, v107
	s_waitcnt lgkmcnt(0)
	v_add_f32_e32 v107, v107, v109
	v_fmamk_f32 v107, v107, 0x3c2aaaab, v1
	v_mul_f32_e32 v109, 0x4b800000, v107
	v_cmp_gt_f32_e32 vcc, s56, v107
	s_nop 1
	v_cndmask_b32_e32 v107, v107, v109, vcc
	v_rsq_f32_e32 v109, v107
	v_mad_i64_i32 v[106:107], s[30:31], v106, s57, v[114:115]
	v_lshl_add_u64 v[106:107], v[140:141], 1, v[106:107]
	v_mul_f32_e32 v116, 0x45800000, v109
	v_cndmask_b32_e32 v116, v109, v116, vcc
	v_mul_f32_e32 v94, v94, v116
	v_mul_f32_e32 v95, v95, v116
	v_lshl_add_u64 v[114:115], v[106:107], 0, v[126:127]
	v_mul_f32_e32 v96, v96, v116
	v_mul_f32_e32 v97, v97, v116
	v_mul_f32_e32 v90, v90, v116
	v_mul_f32_e32 v91, v91, v116
	v_mul_f32_e32 v92, v92, v116
	v_mul_f32_e32 v93, v93, v116
	v_mul_f32_e32 v86, v86, v116
	v_mul_f32_e32 v87, v87, v116
	v_mul_f32_e32 v88, v88, v116
	v_mul_f32_e32 v89, v89, v116
	v_mul_f32_e32 v82, v82, v116
	v_mul_f32_e32 v83, v83, v116
	v_mul_f32_e32 v84, v84, v116
	v_mul_f32_e32 v85, v85, v116
	s_and_b64 vcc, exec, s[6:7]
	v_mul_f32_e32 v94, v170, v94
	v_mul_f32_e32 v95, v171, v95
	v_mul_f32_e32 v96, v172, v96
	v_mul_f32_e32 v97, v173, v97
	v_cvt_pk_bf16_f32 v94, v94, v95
	v_cvt_pk_bf16_f32 v95, v96, v97
	global_store_dwordx2 v[114:115], v[94:95], off
	v_mul_f32_e32 v90, v174, v90
	v_mul_f32_e32 v91, v175, v91
	v_mul_f32_e32 v92, v176, v92
	v_mul_f32_e32 v93, v177, v93
	v_cvt_pk_bf16_f32 v90, v90, v91
	v_cvt_pk_bf16_f32 v91, v92, v93
	global_store_dwordx2 v[114:115], v[90:91], off offset:32
	v_mul_f32_e32 v86, v178, v86
	v_mul_f32_e32 v87, v179, v87
	v_mul_f32_e32 v88, v180, v88
	v_mul_f32_e32 v89, v89, v181
	v_cvt_pk_bf16_f32 v86, v86, v87
	v_cvt_pk_bf16_f32 v87, v88, v89
	global_store_dwordx2 v[114:115], v[86:87], off offset:64
	v_mul_f32_e32 v82, v82, v182
	v_mul_f32_e32 v83, v83, v183
	v_mul_f32_e32 v84, v84, v184
	v_mul_f32_e32 v85, v85, v185
	v_cvt_pk_bf16_f32 v82, v82, v83
	v_cvt_pk_bf16_f32 v83, v84, v85
	global_store_dwordx2 v[114:115], v[82:83], off offset:96
	s_nop 0
	v_mov_b32_e32 v82, v186
	v_mov_b32_e32 v83, v187
	v_mov_b32_e32 v84, v188
	v_mov_b32_e32 v85, v189
	v_pk_mul_f32 v[82:83], v[116:117], v[82:83] op_sel_hi:[0,1]
	v_pk_mul_f32 v[84:85], v[116:117], v[84:85] op_sel_hi:[0,1]
	v_pk_mul_f32 v[90:91], v[116:117], v[190:191] op_sel_hi:[0,1]
	v_pk_mul_f32 v[92:93], v[116:117], v[192:193] op_sel_hi:[0,1]
	v_pk_mul_f32 v[88:89], v[98:99], v[82:83]
	v_pk_mul_f32 v[86:87], v[100:101], v[84:85]
	v_pk_mul_f32 v[84:85], v[102:103], v[90:91]
	v_pk_mul_f32 v[82:83], v[104:105], v[92:93]
	s_cbranch_vccnz .LBB0_642
	v_add_u32_e32 v90, s60, v108
	v_ashrrev_i32_e32 v91, 6, v90
	v_and_b32_e32 v90, 63, v90
	v_cndmask_b32_e64 v90, v90, v91, s[4:5]
	v_cvt_f32_i32_e32 v98, v90
	ds_bpermute_b32 v90, v146, v88
	ds_bpermute_b32 v91, v146, v89
	v_mul_f32_e32 v93, 0x3ea1e89b, v98
	v_mul_f32_e32 v94, 0.15915494, v98
	v_mul_f32_e32 v95, 0.15915494, v93
	v_sin_f32_e32 v92, v94
	v_sin_f32_e32 v93, v95
	v_mul_f32_e32 v97, 0x3d0186e3, v98
	v_mul_f32_e32 v100, 0.15915494, v97
	v_cos_f32_e32 v94, v94
	s_waitcnt lgkmcnt(0)
	v_pk_mul_f32 v[90:91], v[92:93], v[90:91]
	v_mul_f32_e32 v93, 0x3dcccccd, v98
	ds_bpermute_b32 v92, v146, v86
	v_mul_f32_e32 v99, 0.15915494, v93
	ds_bpermute_b32 v93, v146, v87
	v_cos_f32_e32 v95, v95
	v_sin_f32_e32 v96, v99
	v_sin_f32_e32 v97, v100
	v_cndmask_b32_e64 v91, v91, -v91, s[2:3]
	v_cndmask_b32_e64 v90, v90, -v90, s[2:3]
	v_pk_fma_f32 v[88:89], v[94:95], v[88:89], v[90:91]
	s_waitcnt lgkmcnt(0)
	v_pk_mul_f32 v[92:93], v[96:97], v[92:93]
	v_mul_f32_e32 v95, 0x3c23d70b, v98
	v_mul_f32_e32 v97, 0x3b4f3e39, v98
	v_cos_f32_e32 v90, v99
	v_cos_f32_e32 v91, v100
	ds_bpermute_b32 v94, v146, v84
	v_mul_f32_e32 v99, 0.15915494, v95
	ds_bpermute_b32 v95, v146, v85
	v_mul_f32_e32 v100, 0.15915494, v97
	v_sin_f32_e32 v96, v99
	v_sin_f32_e32 v97, v100
	v_cndmask_b32_e64 v93, v93, -v93, s[2:3]
	v_cndmask_b32_e64 v92, v92, -v92, s[2:3]
	v_pk_fma_f32 v[86:87], v[90:91], v[86:87], v[92:93]
	v_cos_f32_e32 v90, v99
	v_cos_f32_e32 v91, v100
	s_waitcnt lgkmcnt(0)
	v_pk_mul_f32 v[92:93], v[96:97], v[94:95]
	v_mul_f32_e32 v95, 0x3a831270, v98
	v_mul_f32_e32 v97, 0x39a5cb61, v98
	ds_bpermute_b32 v94, v146, v82
	v_mul_f32_e32 v99, 0.15915494, v95
	ds_bpermute_b32 v95, v146, v83
	v_mul_f32_e32 v98, 0.15915494, v97
	v_sin_f32_e32 v96, v99
	v_sin_f32_e32 v97, v98
	v_cndmask_b32_e64 v93, v93, -v93, s[2:3]
	v_cndmask_b32_e64 v92, v92, -v92, s[2:3]
	v_pk_fma_f32 v[84:85], v[90:91], v[84:85], v[92:93]
	v_cos_f32_e32 v90, v99
	v_cos_f32_e32 v91, v98
	s_waitcnt lgkmcnt(0)
	v_pk_mul_f32 v[92:93], v[96:97], v[94:95]
	s_nop 0
	v_cndmask_b32_e64 v93, v93, -v93, s[2:3]
	v_cndmask_b32_e64 v92, v92, -v92, s[2:3]
	v_pk_fma_f32 v[82:83], v[90:91], v[82:83], v[92:93]

.LBB0_648:
	v_mul_f32_e32 v91, v79, v79
	v_fmac_f32_e32 v91, v78, v78
	v_fmac_f32_e32 v91, v80, v80
	v_fmac_f32_e32 v91, v81, v81
	v_fmac_f32_e32 v91, v74, v74
	v_fmac_f32_e32 v91, v75, v75
	v_fmac_f32_e32 v91, v76, v76
	v_fmac_f32_e32 v91, v77, v77
	v_fmac_f32_e32 v91, v70, v70
	v_fmac_f32_e32 v91, v71, v71
	v_fmac_f32_e32 v91, v72, v72
	v_fmac_f32_e32 v91, v73, v73
	v_fmac_f32_e32 v91, v66, v66
	v_fmac_f32_e32 v91, v67, v67
	v_fmac_f32_e32 v91, v68, v68
	s_waitcnt vmcnt(0)
	v_pk_mul_f32 v[98:99], v[82:83], v[82:83]
	v_fmac_f32_e32 v91, v69, v69
	v_add_f32_e32 v91, v91, v98
	v_pk_mul_f32 v[100:101], v[84:85], v[84:85]
	v_add_f32_e32 v91, v99, v91
	v_add_f32_e32 v91, v100, v91
	v_pk_mul_f32 v[102:103], v[86:87], v[86:87]
	v_add_f32_e32 v91, v101, v91
	v_add_f32_e32 v91, v102, v91
	v_pk_mul_f32 v[104:105], v[88:89], v[88:89]
	v_add_f32_e32 v91, v103, v91
	v_add_f32_e32 v91, v104, v91
	v_add_f32_e32 v91, v105, v91
	ds_bpermute_b32 v93, v146, v91
	v_mov_b64_e32 v[98:99], s[24:25]
	v_mov_b32_e32 v127, v163
	s_waitcnt lgkmcnt(0)
	v_add_f32_e32 v91, v91, v93
	ds_bpermute_b32 v93, v148, v91
	s_waitcnt lgkmcnt(0)
	v_add_f32_e32 v91, v91, v93
	v_fmamk_f32 v91, v91, 0x3c2aaaab, v1
	v_mul_f32_e32 v93, 0x4b800000, v91
	v_cmp_gt_f32_e32 vcc, s56, v91
	s_nop 1
	v_cndmask_b32_e32 v91, v91, v93, vcc
	v_rsq_f32_e32 v93, v91
	v_mad_i64_i32 v[90:91], s[30:31], v90, s57, v[98:99]
	v_lshl_add_u64 v[90:91], v[140:141], 1, v[90:91]
	v_mul_f32_e32 v100, 0x45800000, v93
	v_cndmask_b32_e32 v100, v93, v100, vcc
	v_mul_f32_e32 v78, v78, v100
	v_mul_f32_e32 v79, v79, v100
	v_lshl_add_u64 v[98:99], v[90:91], 0, v[126:127]
	v_mul_f32_e32 v80, v80, v100
	v_mul_f32_e32 v81, v81, v100
	v_mul_f32_e32 v74, v74, v100
	v_mul_f32_e32 v75, v75, v100
	v_mul_f32_e32 v76, v76, v100
	v_mul_f32_e32 v77, v77, v100
	v_mul_f32_e32 v70, v70, v100
	v_mul_f32_e32 v71, v71, v100
	v_mul_f32_e32 v72, v72, v100
	v_mul_f32_e32 v73, v73, v100
	v_mul_f32_e32 v66, v66, v100
	v_mul_f32_e32 v67, v67, v100
	v_mul_f32_e32 v68, v68, v100
	v_mul_f32_e32 v69, v69, v100
	s_and_b64 vcc, exec, s[6:7]
	v_mul_f32_e32 v78, v170, v78
	v_mul_f32_e32 v79, v171, v79
	v_mul_f32_e32 v80, v172, v80
	v_mul_f32_e32 v81, v173, v81
	v_cvt_pk_bf16_f32 v78, v78, v79
	v_cvt_pk_bf16_f32 v79, v80, v81
	global_store_dwordx2 v[98:99], v[78:79], off
	v_mul_f32_e32 v74, v174, v74
	v_mul_f32_e32 v75, v175, v75
	v_mul_f32_e32 v76, v176, v76
	v_mul_f32_e32 v77, v177, v77
	v_cvt_pk_bf16_f32 v74, v74, v75
	v_cvt_pk_bf16_f32 v75, v76, v77
	global_store_dwordx2 v[98:99], v[74:75], off offset:32
	v_mul_f32_e32 v70, v178, v70
	v_mul_f32_e32 v71, v179, v71
	v_mul_f32_e32 v72, v180, v72
	v_mul_f32_e32 v73, v73, v181
	v_cvt_pk_bf16_f32 v70, v70, v71
	v_cvt_pk_bf16_f32 v71, v72, v73
	global_store_dwordx2 v[98:99], v[70:71], off offset:64
	v_mul_f32_e32 v66, v66, v182
	v_mul_f32_e32 v67, v67, v183
	v_mul_f32_e32 v68, v68, v184
	v_mul_f32_e32 v69, v69, v185
	v_cvt_pk_bf16_f32 v66, v66, v67
	v_cvt_pk_bf16_f32 v67, v68, v69
	global_store_dwordx2 v[98:99], v[66:67], off offset:96
	s_nop 0
	v_mov_b32_e32 v66, v186
	v_mov_b32_e32 v67, v187
	v_mov_b32_e32 v68, v188
	v_mov_b32_e32 v69, v189
	v_pk_mul_f32 v[66:67], v[100:101], v[66:67] op_sel_hi:[0,1]
	v_pk_mul_f32 v[68:69], v[100:101], v[68:69] op_sel_hi:[0,1]
	v_pk_mul_f32 v[74:75], v[100:101], v[190:191] op_sel_hi:[0,1]
	v_pk_mul_f32 v[76:77], v[100:101], v[192:193] op_sel_hi:[0,1]
	v_pk_mul_f32 v[72:73], v[82:83], v[66:67]
	v_pk_mul_f32 v[70:71], v[84:85], v[68:69]
	v_pk_mul_f32 v[68:69], v[86:87], v[74:75]
	v_pk_mul_f32 v[66:67], v[88:89], v[76:77]
	s_cbranch_vccnz .LBB0_650
	v_add_u32_e32 v74, s60, v92
	v_ashrrev_i32_e32 v75, 6, v74
	v_and_b32_e32 v74, 63, v74
	v_cndmask_b32_e64 v74, v74, v75, s[4:5]
	v_cvt_f32_i32_e32 v82, v74
	ds_bpermute_b32 v74, v146, v72
	ds_bpermute_b32 v75, v146, v73
	v_mul_f32_e32 v77, 0x3ea1e89b, v82
	v_mul_f32_e32 v78, 0.15915494, v82
	v_mul_f32_e32 v79, 0.15915494, v77
	v_sin_f32_e32 v76, v78
	v_sin_f32_e32 v77, v79
	v_mul_f32_e32 v81, 0x3d0186e3, v82
	v_mul_f32_e32 v84, 0.15915494, v81
	v_cos_f32_e32 v78, v78
	s_waitcnt lgkmcnt(0)
	v_pk_mul_f32 v[74:75], v[76:77], v[74:75]
	v_mul_f32_e32 v77, 0x3dcccccd, v82
	ds_bpermute_b32 v76, v146, v70
	v_mul_f32_e32 v83, 0.15915494, v77
	ds_bpermute_b32 v77, v146, v71
	v_cos_f32_e32 v79, v79
	v_sin_f32_e32 v80, v83
	v_sin_f32_e32 v81, v84
	v_cndmask_b32_e64 v75, v75, -v75, s[2:3]
	v_cndmask_b32_e64 v74, v74, -v74, s[2:3]
	v_pk_fma_f32 v[72:73], v[78:79], v[72:73], v[74:75]
	s_waitcnt lgkmcnt(0)
	v_pk_mul_f32 v[76:77], v[80:81], v[76:77]
	v_mul_f32_e32 v79, 0x3c23d70b, v82
	v_mul_f32_e32 v81, 0x3b4f3e39, v82
	v_cos_f32_e32 v74, v83
	v_cos_f32_e32 v75, v84
	ds_bpermute_b32 v78, v146, v68
	v_mul_f32_e32 v83, 0.15915494, v79
	ds_bpermute_b32 v79, v146, v69
	v_mul_f32_e32 v84, 0.15915494, v81
	v_sin_f32_e32 v80, v83
	v_sin_f32_e32 v81, v84
	v_cndmask_b32_e64 v77, v77, -v77, s[2:3]
	v_cndmask_b32_e64 v76, v76, -v76, s[2:3]
	v_pk_fma_f32 v[70:71], v[74:75], v[70:71], v[76:77]
	v_cos_f32_e32 v74, v83
	v_cos_f32_e32 v75, v84
	s_waitcnt lgkmcnt(0)
	v_pk_mul_f32 v[76:77], v[80:81], v[78:79]
	v_mul_f32_e32 v79, 0x3a831270, v82
	v_mul_f32_e32 v81, 0x39a5cb61, v82
	ds_bpermute_b32 v78, v146, v66
	v_mul_f32_e32 v83, 0.15915494, v79
	ds_bpermute_b32 v79, v146, v67
	v_mul_f32_e32 v82, 0.15915494, v81
	v_sin_f32_e32 v80, v83
	v_sin_f32_e32 v81, v82
	v_cndmask_b32_e64 v77, v77, -v77, s[2:3]
	v_cndmask_b32_e64 v76, v76, -v76, s[2:3]
	v_pk_fma_f32 v[68:69], v[74:75], v[68:69], v[76:77]
	v_cos_f32_e32 v74, v83
	v_cos_f32_e32 v75, v82
	s_waitcnt lgkmcnt(0)
	v_pk_mul_f32 v[76:77], v[80:81], v[78:79]
	s_nop 0
	v_cndmask_b32_e64 v77, v77, -v77, s[2:3]
	v_cndmask_b32_e64 v76, v76, -v76, s[2:3]
	v_pk_fma_f32 v[66:67], v[74:75], v[66:67], v[76:77]

.LBB0_656:
	v_mul_f32_e32 v75, v63, v63
	v_fmac_f32_e32 v75, v62, v62
	v_fmac_f32_e32 v75, v64, v64
	v_fmac_f32_e32 v75, v65, v65
	v_fmac_f32_e32 v75, v58, v58
	v_fmac_f32_e32 v75, v59, v59
	v_fmac_f32_e32 v75, v60, v60
	v_fmac_f32_e32 v75, v61, v61
	v_fmac_f32_e32 v75, v54, v54
	v_fmac_f32_e32 v75, v55, v55
	v_fmac_f32_e32 v75, v56, v56
	v_fmac_f32_e32 v75, v57, v57
	v_fmac_f32_e32 v75, v50, v50
	v_fmac_f32_e32 v75, v51, v51
	v_fmac_f32_e32 v75, v52, v52
	s_waitcnt vmcnt(0)
	v_pk_mul_f32 v[82:83], v[66:67], v[66:67]
	v_fmac_f32_e32 v75, v53, v53
	v_add_f32_e32 v75, v75, v82
	v_pk_mul_f32 v[84:85], v[68:69], v[68:69]
	v_add_f32_e32 v75, v83, v75
	v_add_f32_e32 v75, v84, v75
	v_pk_mul_f32 v[86:87], v[70:71], v[70:71]
	v_add_f32_e32 v75, v85, v75
	v_add_f32_e32 v75, v86, v75
	v_pk_mul_f32 v[88:89], v[72:73], v[72:73]
	v_add_f32_e32 v75, v87, v75
	v_add_f32_e32 v75, v88, v75
	v_add_f32_e32 v75, v89, v75
	ds_bpermute_b32 v77, v146, v75
	v_mov_b64_e32 v[82:83], s[24:25]
	v_mov_b32_e32 v127, v163
	s_waitcnt lgkmcnt(0)
	v_add_f32_e32 v75, v75, v77
	ds_bpermute_b32 v77, v148, v75
	s_waitcnt lgkmcnt(0)
	v_add_f32_e32 v75, v75, v77
	v_fmamk_f32 v75, v75, 0x3c2aaaab, v1
	v_mul_f32_e32 v77, 0x4b800000, v75
	v_cmp_gt_f32_e32 vcc, s56, v75
	s_nop 1
	v_cndmask_b32_e32 v75, v75, v77, vcc
	v_rsq_f32_e32 v77, v75
	v_mad_i64_i32 v[74:75], s[30:31], v74, s57, v[82:83]
	v_lshl_add_u64 v[74:75], v[140:141], 1, v[74:75]
	v_mul_f32_e32 v84, 0x45800000, v77
	v_cndmask_b32_e32 v84, v77, v84, vcc
	v_mul_f32_e32 v62, v62, v84
	v_mul_f32_e32 v63, v63, v84
	v_lshl_add_u64 v[82:83], v[74:75], 0, v[126:127]
	v_mul_f32_e32 v64, v64, v84
	v_mul_f32_e32 v65, v65, v84
	v_mul_f32_e32 v58, v58, v84
	v_mul_f32_e32 v59, v59, v84
	v_mul_f32_e32 v60, v60, v84
	v_mul_f32_e32 v61, v61, v84
	v_mul_f32_e32 v54, v54, v84
	v_mul_f32_e32 v55, v55, v84
	v_mul_f32_e32 v56, v56, v84
	v_mul_f32_e32 v57, v57, v84
	v_mul_f32_e32 v50, v50, v84
	v_mul_f32_e32 v51, v51, v84
	v_mul_f32_e32 v52, v52, v84
	v_mul_f32_e32 v53, v53, v84
	s_and_b64 vcc, exec, s[6:7]
	v_mul_f32_e32 v62, v170, v62
	v_mul_f32_e32 v63, v171, v63
	v_mul_f32_e32 v64, v172, v64
	v_mul_f32_e32 v65, v173, v65
	v_cvt_pk_bf16_f32 v62, v62, v63
	v_cvt_pk_bf16_f32 v63, v64, v65
	global_store_dwordx2 v[82:83], v[62:63], off
	v_mul_f32_e32 v58, v174, v58
	v_mul_f32_e32 v59, v175, v59
	v_mul_f32_e32 v60, v176, v60
	v_mul_f32_e32 v61, v177, v61
	v_cvt_pk_bf16_f32 v58, v58, v59
	v_cvt_pk_bf16_f32 v59, v60, v61
	global_store_dwordx2 v[82:83], v[58:59], off offset:32
	v_mul_f32_e32 v54, v178, v54
	v_mul_f32_e32 v55, v179, v55
	v_mul_f32_e32 v56, v180, v56
	v_mul_f32_e32 v57, v57, v181
	v_cvt_pk_bf16_f32 v54, v54, v55
	v_cvt_pk_bf16_f32 v55, v56, v57
	global_store_dwordx2 v[82:83], v[54:55], off offset:64
	v_mul_f32_e32 v50, v50, v182
	v_mul_f32_e32 v51, v51, v183
	v_mul_f32_e32 v52, v52, v184
	v_mul_f32_e32 v53, v53, v185
	v_cvt_pk_bf16_f32 v50, v50, v51
	v_cvt_pk_bf16_f32 v51, v52, v53
	global_store_dwordx2 v[82:83], v[50:51], off offset:96
	s_nop 0
	v_mov_b32_e32 v50, v186
	v_mov_b32_e32 v51, v187
	v_mov_b32_e32 v52, v188
	v_mov_b32_e32 v53, v189
	v_pk_mul_f32 v[50:51], v[84:85], v[50:51] op_sel_hi:[0,1]
	v_pk_mul_f32 v[52:53], v[84:85], v[52:53] op_sel_hi:[0,1]
	v_pk_mul_f32 v[58:59], v[84:85], v[190:191] op_sel_hi:[0,1]
	v_pk_mul_f32 v[60:61], v[84:85], v[192:193] op_sel_hi:[0,1]
	v_pk_mul_f32 v[56:57], v[66:67], v[50:51]
	v_pk_mul_f32 v[54:55], v[68:69], v[52:53]
	v_pk_mul_f32 v[52:53], v[70:71], v[58:59]
	v_pk_mul_f32 v[50:51], v[72:73], v[60:61]
	s_cbranch_vccnz .LBB0_658
	v_add_u32_e32 v58, s60, v76
	v_ashrrev_i32_e32 v59, 6, v58
	v_and_b32_e32 v58, 63, v58
	v_cndmask_b32_e64 v58, v58, v59, s[4:5]
	v_cvt_f32_i32_e32 v66, v58
	ds_bpermute_b32 v58, v146, v56
	ds_bpermute_b32 v59, v146, v57
	v_mul_f32_e32 v61, 0x3ea1e89b, v66
	v_mul_f32_e32 v62, 0.15915494, v66
	v_mul_f32_e32 v63, 0.15915494, v61
	v_sin_f32_e32 v60, v62
	v_sin_f32_e32 v61, v63
	v_mul_f32_e32 v65, 0x3d0186e3, v66
	v_mul_f32_e32 v68, 0.15915494, v65
	v_cos_f32_e32 v62, v62
	s_waitcnt lgkmcnt(0)
	v_pk_mul_f32 v[58:59], v[60:61], v[58:59]
	v_mul_f32_e32 v61, 0x3dcccccd, v66
	ds_bpermute_b32 v60, v146, v54
	v_mul_f32_e32 v67, 0.15915494, v61
	ds_bpermute_b32 v61, v146, v55
	v_cos_f32_e32 v63, v63
	v_sin_f32_e32 v64, v67
	v_sin_f32_e32 v65, v68
	v_cndmask_b32_e64 v59, v59, -v59, s[2:3]
	v_cndmask_b32_e64 v58, v58, -v58, s[2:3]
	v_pk_fma_f32 v[56:57], v[62:63], v[56:57], v[58:59]
	s_waitcnt lgkmcnt(0)
	v_pk_mul_f32 v[60:61], v[64:65], v[60:61]
	v_mul_f32_e32 v63, 0x3c23d70b, v66
	v_mul_f32_e32 v65, 0x3b4f3e39, v66
	v_cos_f32_e32 v58, v67
	v_cos_f32_e32 v59, v68
	ds_bpermute_b32 v62, v146, v52
	v_mul_f32_e32 v67, 0.15915494, v63
	ds_bpermute_b32 v63, v146, v53
	v_mul_f32_e32 v68, 0.15915494, v65
	v_sin_f32_e32 v64, v67
	v_sin_f32_e32 v65, v68
	v_cndmask_b32_e64 v61, v61, -v61, s[2:3]
	v_cndmask_b32_e64 v60, v60, -v60, s[2:3]
	v_pk_fma_f32 v[54:55], v[58:59], v[54:55], v[60:61]
	v_cos_f32_e32 v58, v67
	v_cos_f32_e32 v59, v68
	s_waitcnt lgkmcnt(0)
	v_pk_mul_f32 v[60:61], v[64:65], v[62:63]
	v_mul_f32_e32 v63, 0x3a831270, v66
	v_mul_f32_e32 v65, 0x39a5cb61, v66
	ds_bpermute_b32 v62, v146, v50
	v_mul_f32_e32 v67, 0.15915494, v63
	ds_bpermute_b32 v63, v146, v51
	v_mul_f32_e32 v66, 0.15915494, v65
	v_sin_f32_e32 v64, v67
	v_sin_f32_e32 v65, v66
	v_cndmask_b32_e64 v61, v61, -v61, s[2:3]
	v_cndmask_b32_e64 v60, v60, -v60, s[2:3]
	v_pk_fma_f32 v[52:53], v[58:59], v[52:53], v[60:61]
	v_cos_f32_e32 v58, v67
	v_cos_f32_e32 v59, v66
	s_waitcnt lgkmcnt(0)
	v_pk_mul_f32 v[60:61], v[64:65], v[62:63]
	s_nop 0
	v_cndmask_b32_e64 v61, v61, -v61, s[2:3]
	v_cndmask_b32_e64 v60, v60, -v60, s[2:3]
	v_pk_fma_f32 v[50:51], v[58:59], v[50:51], v[60:61]

.LBB0_664:
	v_mul_f32_e32 v59, v47, v47
	v_fmac_f32_e32 v59, v46, v46
	v_fmac_f32_e32 v59, v48, v48
	v_fmac_f32_e32 v59, v49, v49
	v_fmac_f32_e32 v59, v42, v42
	v_fmac_f32_e32 v59, v43, v43
	v_fmac_f32_e32 v59, v44, v44
	v_fmac_f32_e32 v59, v45, v45
	v_fmac_f32_e32 v59, v38, v38
	v_fmac_f32_e32 v59, v39, v39
	v_fmac_f32_e32 v59, v40, v40
	v_fmac_f32_e32 v59, v41, v41
	v_fmac_f32_e32 v59, v34, v34
	v_fmac_f32_e32 v59, v35, v35
	v_fmac_f32_e32 v59, v36, v36
	s_waitcnt vmcnt(0)
	v_pk_mul_f32 v[66:67], v[50:51], v[50:51]
	v_fmac_f32_e32 v59, v37, v37
	v_add_f32_e32 v59, v59, v66
	v_pk_mul_f32 v[68:69], v[52:53], v[52:53]
	v_add_f32_e32 v59, v67, v59
	v_add_f32_e32 v59, v68, v59
	v_pk_mul_f32 v[70:71], v[54:55], v[54:55]
	v_add_f32_e32 v59, v69, v59
	v_add_f32_e32 v59, v70, v59
	v_pk_mul_f32 v[72:73], v[56:57], v[56:57]
	v_add_f32_e32 v59, v71, v59
	v_add_f32_e32 v59, v72, v59
	v_add_f32_e32 v59, v73, v59
	ds_bpermute_b32 v61, v146, v59
	v_mov_b64_e32 v[66:67], s[24:25]
	v_mov_b32_e32 v127, v163
	s_waitcnt lgkmcnt(0)
	v_add_f32_e32 v59, v59, v61
	ds_bpermute_b32 v61, v148, v59
	s_waitcnt lgkmcnt(0)
	v_add_f32_e32 v59, v59, v61
	v_fmamk_f32 v59, v59, 0x3c2aaaab, v1
	v_mul_f32_e32 v61, 0x4b800000, v59
	v_cmp_gt_f32_e32 vcc, s56, v59
	s_nop 1
	v_cndmask_b32_e32 v59, v59, v61, vcc
	v_rsq_f32_e32 v61, v59
	v_mad_i64_i32 v[58:59], s[30:31], v58, s57, v[66:67]
	v_lshl_add_u64 v[58:59], v[140:141], 1, v[58:59]
	v_mul_f32_e32 v68, 0x45800000, v61
	v_cndmask_b32_e32 v68, v61, v68, vcc
	v_mul_f32_e32 v46, v46, v68
	v_mul_f32_e32 v47, v47, v68
	v_lshl_add_u64 v[66:67], v[58:59], 0, v[126:127]
	v_mul_f32_e32 v48, v48, v68
	v_mul_f32_e32 v49, v49, v68
	v_mul_f32_e32 v42, v42, v68
	v_mul_f32_e32 v43, v43, v68
	v_mul_f32_e32 v44, v44, v68
	v_mul_f32_e32 v45, v45, v68
	v_mul_f32_e32 v38, v38, v68
	v_mul_f32_e32 v39, v39, v68
	v_mul_f32_e32 v40, v40, v68
	v_mul_f32_e32 v41, v41, v68
	v_mul_f32_e32 v34, v34, v68
	v_mul_f32_e32 v35, v35, v68
	v_mul_f32_e32 v36, v36, v68
	v_mul_f32_e32 v37, v37, v68
	s_and_b64 vcc, exec, s[6:7]
	v_mul_f32_e32 v46, v170, v46
	v_mul_f32_e32 v47, v171, v47
	v_mul_f32_e32 v48, v172, v48
	v_mul_f32_e32 v49, v173, v49
	v_cvt_pk_bf16_f32 v46, v46, v47
	v_cvt_pk_bf16_f32 v47, v48, v49
	global_store_dwordx2 v[66:67], v[46:47], off
	v_mul_f32_e32 v42, v174, v42
	v_mul_f32_e32 v43, v175, v43
	v_mul_f32_e32 v44, v176, v44
	v_mul_f32_e32 v45, v177, v45
	v_cvt_pk_bf16_f32 v42, v42, v43
	v_cvt_pk_bf16_f32 v43, v44, v45
	global_store_dwordx2 v[66:67], v[42:43], off offset:32
	v_mul_f32_e32 v38, v178, v38
	v_mul_f32_e32 v39, v179, v39
	v_mul_f32_e32 v40, v180, v40
	v_mul_f32_e32 v41, v41, v181
	v_cvt_pk_bf16_f32 v38, v38, v39
	v_cvt_pk_bf16_f32 v39, v40, v41
	global_store_dwordx2 v[66:67], v[38:39], off offset:64
	v_mul_f32_e32 v34, v34, v182
	v_mul_f32_e32 v35, v35, v183
	v_mul_f32_e32 v36, v36, v184
	v_mul_f32_e32 v37, v37, v185
	v_cvt_pk_bf16_f32 v34, v34, v35
	v_cvt_pk_bf16_f32 v35, v36, v37
	global_store_dwordx2 v[66:67], v[34:35], off offset:96
	s_nop 0
	v_mov_b32_e32 v34, v186
	v_mov_b32_e32 v35, v187
	v_mov_b32_e32 v36, v188
	v_mov_b32_e32 v37, v189
	v_pk_mul_f32 v[34:35], v[68:69], v[34:35] op_sel_hi:[0,1]
	v_pk_mul_f32 v[36:37], v[68:69], v[36:37] op_sel_hi:[0,1]
	v_pk_mul_f32 v[42:43], v[68:69], v[190:191] op_sel_hi:[0,1]
	v_pk_mul_f32 v[44:45], v[68:69], v[192:193] op_sel_hi:[0,1]
	v_pk_mul_f32 v[40:41], v[50:51], v[34:35]
	v_pk_mul_f32 v[38:39], v[52:53], v[36:37]
	v_pk_mul_f32 v[36:37], v[54:55], v[42:43]
	v_pk_mul_f32 v[34:35], v[56:57], v[44:45]
	s_cbranch_vccnz .LBB0_666
	v_add_u32_e32 v42, s60, v60
	v_ashrrev_i32_e32 v43, 6, v42
	v_and_b32_e32 v42, 63, v42
	v_cndmask_b32_e64 v42, v42, v43, s[4:5]
	v_cvt_f32_i32_e32 v50, v42
	ds_bpermute_b32 v42, v146, v40
	ds_bpermute_b32 v43, v146, v41
	v_mul_f32_e32 v45, 0x3ea1e89b, v50
	v_mul_f32_e32 v46, 0.15915494, v50
	v_mul_f32_e32 v47, 0.15915494, v45
	v_sin_f32_e32 v44, v46
	v_sin_f32_e32 v45, v47
	v_mul_f32_e32 v49, 0x3d0186e3, v50
	v_mul_f32_e32 v52, 0.15915494, v49
	v_cos_f32_e32 v46, v46
	s_waitcnt lgkmcnt(0)
	v_pk_mul_f32 v[42:43], v[44:45], v[42:43]
	v_mul_f32_e32 v45, 0x3dcccccd, v50
	ds_bpermute_b32 v44, v146, v38
	v_mul_f32_e32 v51, 0.15915494, v45
	ds_bpermute_b32 v45, v146, v39
	v_cos_f32_e32 v47, v47
	v_sin_f32_e32 v48, v51
	v_sin_f32_e32 v49, v52
	v_cndmask_b32_e64 v43, v43, -v43, s[2:3]
	v_cndmask_b32_e64 v42, v42, -v42, s[2:3]
	v_pk_fma_f32 v[40:41], v[46:47], v[40:41], v[42:43]
	s_waitcnt lgkmcnt(0)
	v_pk_mul_f32 v[44:45], v[48:49], v[44:45]
	v_mul_f32_e32 v47, 0x3c23d70b, v50
	v_mul_f32_e32 v49, 0x3b4f3e39, v50
	v_cos_f32_e32 v42, v51
	v_cos_f32_e32 v43, v52
	ds_bpermute_b32 v46, v146, v36
	v_mul_f32_e32 v51, 0.15915494, v47
	ds_bpermute_b32 v47, v146, v37
	v_mul_f32_e32 v52, 0.15915494, v49
	v_sin_f32_e32 v48, v51
	v_sin_f32_e32 v49, v52
	v_cndmask_b32_e64 v45, v45, -v45, s[2:3]
	v_cndmask_b32_e64 v44, v44, -v44, s[2:3]
	v_pk_fma_f32 v[38:39], v[42:43], v[38:39], v[44:45]
	v_cos_f32_e32 v42, v51
	v_cos_f32_e32 v43, v52
	s_waitcnt lgkmcnt(0)
	v_pk_mul_f32 v[44:45], v[48:49], v[46:47]
	v_mul_f32_e32 v47, 0x3a831270, v50
	v_mul_f32_e32 v49, 0x39a5cb61, v50
	ds_bpermute_b32 v46, v146, v34
	v_mul_f32_e32 v51, 0.15915494, v47
	ds_bpermute_b32 v47, v146, v35
	v_mul_f32_e32 v50, 0.15915494, v49
	v_sin_f32_e32 v48, v51
	v_sin_f32_e32 v49, v50
	v_cndmask_b32_e64 v45, v45, -v45, s[2:3]
	v_cndmask_b32_e64 v44, v44, -v44, s[2:3]
	v_pk_fma_f32 v[36:37], v[42:43], v[36:37], v[44:45]
	v_cos_f32_e32 v42, v51
	v_cos_f32_e32 v43, v50
	s_waitcnt lgkmcnt(0)
	v_pk_mul_f32 v[44:45], v[48:49], v[46:47]
	s_nop 0
	v_cndmask_b32_e64 v45, v45, -v45, s[2:3]
	v_cndmask_b32_e64 v44, v44, -v44, s[2:3]
	v_pk_fma_f32 v[34:35], v[42:43], v[34:35], v[44:45]

.LBB0_672:
	v_mul_f32_e32 v43, v31, v31
	v_fmac_f32_e32 v43, v30, v30
	v_fmac_f32_e32 v43, v32, v32
	v_fmac_f32_e32 v43, v33, v33
	v_fmac_f32_e32 v43, v26, v26
	v_fmac_f32_e32 v43, v27, v27
	v_fmac_f32_e32 v43, v28, v28
	v_fmac_f32_e32 v43, v29, v29
	v_fmac_f32_e32 v43, v22, v22
	v_fmac_f32_e32 v43, v23, v23
	v_fmac_f32_e32 v43, v24, v24
	v_fmac_f32_e32 v43, v25, v25
	v_fmac_f32_e32 v43, v18, v18
	v_fmac_f32_e32 v43, v19, v19
	v_fmac_f32_e32 v43, v20, v20
	s_waitcnt vmcnt(0)
	v_pk_mul_f32 v[50:51], v[34:35], v[34:35]
	v_fmac_f32_e32 v43, v21, v21
	v_add_f32_e32 v43, v43, v50
	v_pk_mul_f32 v[52:53], v[36:37], v[36:37]
	v_add_f32_e32 v43, v51, v43
	v_add_f32_e32 v43, v52, v43
	v_pk_mul_f32 v[54:55], v[38:39], v[38:39]
	v_add_f32_e32 v43, v53, v43
	v_add_f32_e32 v43, v54, v43
	v_pk_mul_f32 v[56:57], v[40:41], v[40:41]
	v_add_f32_e32 v43, v55, v43
	v_add_f32_e32 v43, v56, v43
	v_add_f32_e32 v43, v57, v43
	ds_bpermute_b32 v45, v146, v43
	v_mov_b64_e32 v[50:51], s[24:25]
	v_mov_b32_e32 v127, v163
	s_waitcnt lgkmcnt(0)
	v_add_f32_e32 v43, v43, v45
	ds_bpermute_b32 v45, v148, v43
	s_waitcnt lgkmcnt(0)
	v_add_f32_e32 v43, v43, v45
	v_fmamk_f32 v43, v43, 0x3c2aaaab, v1
	v_mul_f32_e32 v45, 0x4b800000, v43
	v_cmp_gt_f32_e32 vcc, s56, v43
	s_nop 1
	v_cndmask_b32_e32 v43, v43, v45, vcc
	v_rsq_f32_e32 v45, v43
	v_mad_i64_i32 v[42:43], s[30:31], v42, s57, v[50:51]
	v_lshl_add_u64 v[42:43], v[140:141], 1, v[42:43]
	v_mul_f32_e32 v52, 0x45800000, v45
	v_cndmask_b32_e32 v52, v45, v52, vcc
	v_mul_f32_e32 v30, v30, v52
	v_mul_f32_e32 v31, v31, v52
	v_lshl_add_u64 v[50:51], v[42:43], 0, v[126:127]
	v_mul_f32_e32 v32, v32, v52
	v_mul_f32_e32 v33, v33, v52
	v_mul_f32_e32 v26, v26, v52
	v_mul_f32_e32 v27, v27, v52
	v_mul_f32_e32 v28, v28, v52
	v_mul_f32_e32 v29, v29, v52
	v_mul_f32_e32 v22, v22, v52
	v_mul_f32_e32 v23, v23, v52
	v_mul_f32_e32 v24, v24, v52
	v_mul_f32_e32 v25, v25, v52
	v_mul_f32_e32 v18, v18, v52
	v_mul_f32_e32 v19, v19, v52
	v_mul_f32_e32 v20, v20, v52
	v_mul_f32_e32 v21, v21, v52
	s_and_b64 vcc, exec, s[6:7]
	v_mul_f32_e32 v30, v170, v30
	v_mul_f32_e32 v31, v171, v31
	v_mul_f32_e32 v32, v172, v32
	v_mul_f32_e32 v33, v173, v33
	v_cvt_pk_bf16_f32 v30, v30, v31
	v_cvt_pk_bf16_f32 v31, v32, v33
	global_store_dwordx2 v[50:51], v[30:31], off
	v_mul_f32_e32 v26, v174, v26
	v_mul_f32_e32 v27, v175, v27
	v_mul_f32_e32 v28, v176, v28
	v_mul_f32_e32 v29, v177, v29
	v_cvt_pk_bf16_f32 v26, v26, v27
	v_cvt_pk_bf16_f32 v27, v28, v29
	global_store_dwordx2 v[50:51], v[26:27], off offset:32
	v_mul_f32_e32 v22, v178, v22
	v_mul_f32_e32 v23, v179, v23
	v_mul_f32_e32 v24, v180, v24
	v_mul_f32_e32 v25, v25, v181
	v_cvt_pk_bf16_f32 v22, v22, v23
	v_cvt_pk_bf16_f32 v23, v24, v25
	global_store_dwordx2 v[50:51], v[22:23], off offset:64
	v_mul_f32_e32 v18, v18, v182
	v_mul_f32_e32 v19, v19, v183
	v_mul_f32_e32 v20, v20, v184
	v_mul_f32_e32 v21, v21, v185
	v_cvt_pk_bf16_f32 v18, v18, v19
	v_cvt_pk_bf16_f32 v19, v20, v21
	global_store_dwordx2 v[50:51], v[18:19], off offset:96
	s_nop 0
	v_mov_b32_e32 v18, v186
	v_mov_b32_e32 v19, v187
	v_mov_b32_e32 v20, v188
	v_mov_b32_e32 v21, v189
	v_pk_mul_f32 v[18:19], v[52:53], v[18:19] op_sel_hi:[0,1]
	v_pk_mul_f32 v[20:21], v[52:53], v[20:21] op_sel_hi:[0,1]
	v_pk_mul_f32 v[26:27], v[52:53], v[190:191] op_sel_hi:[0,1]
	v_pk_mul_f32 v[28:29], v[52:53], v[192:193] op_sel_hi:[0,1]
	v_pk_mul_f32 v[24:25], v[34:35], v[18:19]
	v_pk_mul_f32 v[22:23], v[36:37], v[20:21]
	v_pk_mul_f32 v[20:21], v[38:39], v[26:27]
	v_pk_mul_f32 v[18:19], v[40:41], v[28:29]
	s_cbranch_vccnz .LBB0_674
	v_add_u32_e32 v26, s60, v44
	v_ashrrev_i32_e32 v27, 6, v26
	v_and_b32_e32 v26, 63, v26
	v_cndmask_b32_e64 v26, v26, v27, s[4:5]
	v_cvt_f32_i32_e32 v34, v26
	ds_bpermute_b32 v26, v146, v24
	ds_bpermute_b32 v27, v146, v25
	v_mul_f32_e32 v29, 0x3ea1e89b, v34
	v_mul_f32_e32 v30, 0.15915494, v34
	v_mul_f32_e32 v31, 0.15915494, v29
	v_sin_f32_e32 v28, v30
	v_sin_f32_e32 v29, v31
	v_mul_f32_e32 v33, 0x3d0186e3, v34
	v_mul_f32_e32 v36, 0.15915494, v33
	v_cos_f32_e32 v30, v30
	s_waitcnt lgkmcnt(0)
	v_pk_mul_f32 v[26:27], v[28:29], v[26:27]
	v_mul_f32_e32 v29, 0x3dcccccd, v34
	ds_bpermute_b32 v28, v146, v22
	v_mul_f32_e32 v35, 0.15915494, v29
	ds_bpermute_b32 v29, v146, v23
	v_cos_f32_e32 v31, v31
	v_sin_f32_e32 v32, v35
	v_sin_f32_e32 v33, v36
	v_cndmask_b32_e64 v27, v27, -v27, s[2:3]
	v_cndmask_b32_e64 v26, v26, -v26, s[2:3]
	v_pk_fma_f32 v[24:25], v[30:31], v[24:25], v[26:27]
	s_waitcnt lgkmcnt(0)
	v_pk_mul_f32 v[28:29], v[32:33], v[28:29]
	v_mul_f32_e32 v31, 0x3c23d70b, v34
	v_mul_f32_e32 v33, 0x3b4f3e39, v34
	v_cos_f32_e32 v26, v35
	v_cos_f32_e32 v27, v36
	ds_bpermute_b32 v30, v146, v20
	v_mul_f32_e32 v35, 0.15915494, v31
	ds_bpermute_b32 v31, v146, v21
	v_mul_f32_e32 v36, 0.15915494, v33
	v_sin_f32_e32 v32, v35
	v_sin_f32_e32 v33, v36
	v_cndmask_b32_e64 v29, v29, -v29, s[2:3]
	v_cndmask_b32_e64 v28, v28, -v28, s[2:3]
	v_pk_fma_f32 v[22:23], v[26:27], v[22:23], v[28:29]
	v_cos_f32_e32 v26, v35
	v_cos_f32_e32 v27, v36
	s_waitcnt lgkmcnt(0)
	v_pk_mul_f32 v[28:29], v[32:33], v[30:31]
	v_mul_f32_e32 v31, 0x3a831270, v34
	v_mul_f32_e32 v33, 0x39a5cb61, v34
	ds_bpermute_b32 v30, v146, v18
	v_mul_f32_e32 v35, 0.15915494, v31
	ds_bpermute_b32 v31, v146, v19
	v_mul_f32_e32 v34, 0.15915494, v33
	v_sin_f32_e32 v32, v35
	v_sin_f32_e32 v33, v34
	v_cndmask_b32_e64 v29, v29, -v29, s[2:3]
	v_cndmask_b32_e64 v28, v28, -v28, s[2:3]
	v_pk_fma_f32 v[20:21], v[26:27], v[20:21], v[28:29]
	v_cos_f32_e32 v26, v35
	v_cos_f32_e32 v27, v34
	s_waitcnt lgkmcnt(0)
	v_pk_mul_f32 v[28:29], v[32:33], v[30:31]
	s_nop 0
	v_cndmask_b32_e64 v29, v29, -v29, s[2:3]
	v_cndmask_b32_e64 v28, v28, -v28, s[2:3]
	v_pk_fma_f32 v[18:19], v[26:27], v[18:19], v[28:29]

.LBB0_680:
	v_mul_f32_e32 v27, v15, v15
	v_fmac_f32_e32 v27, v14, v14
	v_fmac_f32_e32 v27, v16, v16
	v_fmac_f32_e32 v27, v17, v17
	v_fmac_f32_e32 v27, v10, v10
	v_fmac_f32_e32 v27, v11, v11
	v_fmac_f32_e32 v27, v12, v12
	v_fmac_f32_e32 v27, v13, v13
	v_fmac_f32_e32 v27, v6, v6
	v_fmac_f32_e32 v27, v7, v7
	v_fmac_f32_e32 v27, v8, v8
	v_fmac_f32_e32 v27, v9, v9
	v_fmac_f32_e32 v27, v2, v2
	v_fmac_f32_e32 v27, v3, v3
	v_fmac_f32_e32 v27, v4, v4
	s_waitcnt vmcnt(0)
	v_pk_mul_f32 v[34:35], v[18:19], v[18:19]
	v_fmac_f32_e32 v27, v5, v5
	v_add_f32_e32 v27, v27, v34
	v_pk_mul_f32 v[36:37], v[20:21], v[20:21]
	v_add_f32_e32 v27, v35, v27
	v_add_f32_e32 v27, v36, v27
	v_pk_mul_f32 v[38:39], v[22:23], v[22:23]
	v_add_f32_e32 v27, v37, v27
	v_add_f32_e32 v27, v38, v27
	v_pk_mul_f32 v[40:41], v[24:25], v[24:25]
	v_add_f32_e32 v27, v39, v27
	v_add_f32_e32 v27, v40, v27
	v_add_f32_e32 v27, v41, v27
	ds_bpermute_b32 v29, v146, v27
	v_mov_b64_e32 v[34:35], s[24:25]
	v_mov_b32_e32 v127, v163
	s_waitcnt lgkmcnt(0)
	v_add_f32_e32 v27, v27, v29
	ds_bpermute_b32 v29, v148, v27
	s_waitcnt lgkmcnt(0)
	v_add_f32_e32 v27, v27, v29
	v_fmamk_f32 v27, v27, 0x3c2aaaab, v1
	v_mul_f32_e32 v29, 0x4b800000, v27
	v_cmp_gt_f32_e32 vcc, s56, v27
	s_nop 1
	v_cndmask_b32_e32 v27, v27, v29, vcc
	v_rsq_f32_e32 v29, v27
	v_mad_i64_i32 v[26:27], s[30:31], v26, s57, v[34:35]
	v_lshl_add_u64 v[26:27], v[140:141], 1, v[26:27]
	v_mul_f32_e32 v36, 0x45800000, v29
	v_cndmask_b32_e32 v36, v29, v36, vcc
	v_mul_f32_e32 v14, v14, v36
	v_mul_f32_e32 v15, v15, v36
	v_lshl_add_u64 v[34:35], v[26:27], 0, v[126:127]
	v_mul_f32_e32 v16, v16, v36
	v_mul_f32_e32 v17, v17, v36
	v_mul_f32_e32 v10, v10, v36
	v_mul_f32_e32 v11, v11, v36
	v_mul_f32_e32 v12, v12, v36
	v_mul_f32_e32 v13, v13, v36
	v_mul_f32_e32 v6, v6, v36
	v_mul_f32_e32 v7, v7, v36
	v_mul_f32_e32 v8, v8, v36
	v_mul_f32_e32 v9, v9, v36
	v_mul_f32_e32 v2, v2, v36
	v_mul_f32_e32 v3, v3, v36
	v_mul_f32_e32 v4, v4, v36
	v_mul_f32_e32 v5, v5, v36
	s_and_b64 vcc, exec, s[6:7]
	v_mul_f32_e32 v14, v170, v14
	v_mul_f32_e32 v15, v171, v15
	v_mul_f32_e32 v16, v172, v16
	v_mul_f32_e32 v17, v173, v17
	v_cvt_pk_bf16_f32 v14, v14, v15
	v_cvt_pk_bf16_f32 v15, v16, v17
	global_store_dwordx2 v[34:35], v[14:15], off
	v_mul_f32_e32 v10, v174, v10
	v_mul_f32_e32 v11, v175, v11
	v_mul_f32_e32 v12, v176, v12
	v_mul_f32_e32 v13, v177, v13
	v_cvt_pk_bf16_f32 v10, v10, v11
	v_cvt_pk_bf16_f32 v11, v12, v13
	global_store_dwordx2 v[34:35], v[10:11], off offset:32
	v_mul_f32_e32 v6, v178, v6
	v_mul_f32_e32 v7, v179, v7
	v_mul_f32_e32 v8, v180, v8
	v_mul_f32_e32 v9, v9, v181
	v_cvt_pk_bf16_f32 v6, v6, v7
	v_cvt_pk_bf16_f32 v7, v8, v9
	global_store_dwordx2 v[34:35], v[6:7], off offset:64
	v_mul_f32_e32 v2, v2, v182
	v_mul_f32_e32 v3, v3, v183
	v_mul_f32_e32 v4, v4, v184
	v_mul_f32_e32 v5, v5, v185
	v_cvt_pk_bf16_f32 v2, v2, v3
	v_cvt_pk_bf16_f32 v3, v4, v5
	global_store_dwordx2 v[34:35], v[2:3], off offset:96
	s_nop 0
	v_mov_b32_e32 v2, v186
	v_mov_b32_e32 v3, v187
	v_mov_b32_e32 v4, v188
	v_mov_b32_e32 v5, v189
	v_pk_mul_f32 v[2:3], v[36:37], v[2:3] op_sel_hi:[0,1]
	v_pk_mul_f32 v[4:5], v[36:37], v[4:5] op_sel_hi:[0,1]
	v_pk_mul_f32 v[10:11], v[36:37], v[190:191] op_sel_hi:[0,1]
	v_pk_mul_f32 v[12:13], v[36:37], v[192:193] op_sel_hi:[0,1]
	v_pk_mul_f32 v[8:9], v[18:19], v[2:3]
	v_pk_mul_f32 v[6:7], v[20:21], v[4:5]
	v_pk_mul_f32 v[4:5], v[22:23], v[10:11]
	v_pk_mul_f32 v[2:3], v[24:25], v[12:13]
	s_cbranch_vccnz .LBB0_682
	v_add_u32_e32 v10, s60, v28
	v_ashrrev_i32_e32 v11, 6, v10
	v_and_b32_e32 v10, 63, v10
	v_cndmask_b32_e64 v10, v10, v11, s[4:5]
	v_cvt_f32_i32_e32 v18, v10
	ds_bpermute_b32 v10, v146, v8
	ds_bpermute_b32 v11, v146, v9
	v_mul_f32_e32 v13, 0x3ea1e89b, v18
	v_mul_f32_e32 v14, 0.15915494, v18
	v_mul_f32_e32 v15, 0.15915494, v13
	v_sin_f32_e32 v12, v14
	v_sin_f32_e32 v13, v15
	v_mul_f32_e32 v17, 0x3d0186e3, v18
	v_mul_f32_e32 v20, 0.15915494, v17
	v_cos_f32_e32 v14, v14
	s_waitcnt lgkmcnt(0)
	v_pk_mul_f32 v[10:11], v[12:13], v[10:11]
	v_mul_f32_e32 v13, 0x3dcccccd, v18
	ds_bpermute_b32 v12, v146, v6
	v_mul_f32_e32 v19, 0.15915494, v13
	ds_bpermute_b32 v13, v146, v7
	v_cos_f32_e32 v15, v15
	v_sin_f32_e32 v16, v19
	v_sin_f32_e32 v17, v20
	v_cndmask_b32_e64 v11, v11, -v11, s[2:3]
	v_cndmask_b32_e64 v10, v10, -v10, s[2:3]
	v_pk_fma_f32 v[8:9], v[14:15], v[8:9], v[10:11]
	s_waitcnt lgkmcnt(0)
	v_pk_mul_f32 v[12:13], v[16:17], v[12:13]
	v_mul_f32_e32 v15, 0x3c23d70b, v18
	v_mul_f32_e32 v17, 0x3b4f3e39, v18
	v_cos_f32_e32 v10, v19
	v_cos_f32_e32 v11, v20
	ds_bpermute_b32 v14, v146, v4
	v_mul_f32_e32 v19, 0.15915494, v15
	ds_bpermute_b32 v15, v146, v5
	v_mul_f32_e32 v20, 0.15915494, v17
	v_sin_f32_e32 v16, v19
	v_sin_f32_e32 v17, v20
	v_cndmask_b32_e64 v13, v13, -v13, s[2:3]
	v_cndmask_b32_e64 v12, v12, -v12, s[2:3]
	v_pk_fma_f32 v[6:7], v[10:11], v[6:7], v[12:13]
	v_cos_f32_e32 v10, v19
	v_cos_f32_e32 v11, v20
	s_waitcnt lgkmcnt(0)
	v_pk_mul_f32 v[12:13], v[16:17], v[14:15]
	v_mul_f32_e32 v15, 0x3a831270, v18
	v_mul_f32_e32 v17, 0x39a5cb61, v18
	ds_bpermute_b32 v14, v146, v2
	v_mul_f32_e32 v19, 0.15915494, v15
	ds_bpermute_b32 v15, v146, v3
	v_mul_f32_e32 v18, 0.15915494, v17
	v_sin_f32_e32 v16, v19
	v_sin_f32_e32 v17, v18
	v_cndmask_b32_e64 v13, v13, -v13, s[2:3]
	v_cndmask_b32_e64 v12, v12, -v12, s[2:3]
	v_pk_fma_f32 v[4:5], v[10:11], v[4:5], v[12:13]
	v_cos_f32_e32 v10, v19
	v_cos_f32_e32 v11, v18
	s_waitcnt lgkmcnt(0)
	v_pk_mul_f32 v[12:13], v[16:17], v[14:15]
	s_nop 0
	v_cndmask_b32_e64 v13, v13, -v13, s[2:3]
	v_cndmask_b32_e64 v12, v12, -v12, s[2:3]
	v_pk_fma_f32 v[2:3], v[10:11], v[2:3], v[12:13]

.LBB0_1867:
	v_lshlrev_b32_e32 v162, 4, v150
	v_mov_b32_e32 v194, 0x180
	v_bfe_u32 v196, v0, 4, 2
	v_lshlrev_b32_e32 v196, 4, v196
	v_add_u32_e32 v194, v194, v196
	v_mov_b32_e32 v195, 0x280
	v_bfe_u32 v196, v0, 4, 2
	v_lshlrev_b32_e32 v196, 5, v196
	v_add_u32_e32 v195, v195, v196
	global_load_dwordx4 v[170:173], v194, s[20:21]
	global_load_dwordx4 v[174:177], v194, s[20:21] offset:64
	global_load_dwordx4 v[178:181], v194, s[20:21] offset:128
	global_load_dwordx4 v[182:185], v194, s[20:21] offset:192
	global_load_dwordx4 v[186:189], v195, s[20:21]
	global_load_dwordx4 v[190:193], v195, s[20:21] offset:16
	v_mul_f32_e32 v168, v127, v127
	v_fmac_f32_e32 v168, v126, v126
	v_fmac_f32_e32 v168, v128, v128
	v_fmac_f32_e32 v168, v129, v129
	v_fmac_f32_e32 v168, v122, v122
	v_fmac_f32_e32 v168, v123, v123
	v_fmac_f32_e32 v168, v124, v124
	v_fmac_f32_e32 v168, v125, v125
	v_fmac_f32_e32 v168, v118, v118
	v_fmac_f32_e32 v168, v119, v119
	v_fmac_f32_e32 v168, v120, v120
	v_fmac_f32_e32 v168, v121, v121
	v_fmac_f32_e32 v168, v114, v114
	v_fmac_f32_e32 v168, v115, v115
	v_fmac_f32_e32 v168, v116, v116
	s_waitcnt vmcnt(0)
	v_pk_mul_f32 v[140:141], v[130:131], v[130:131]
	v_fmac_f32_e32 v168, v117, v117
	v_add_f32_e32 v140, v168, v140
	v_pk_mul_f32 v[144:145], v[132:133], v[132:133]
	v_add_f32_e32 v140, v141, v140
	v_add_f32_e32 v140, v144, v140
	v_and_b32_e32 v146, 64, v166
	v_pk_mul_f32 v[156:157], v[134:135], v[134:135]
	v_add_f32_e32 v140, v145, v140
	v_xor_b32_e32 v143, 16, v166
	v_add_u32_e32 v169, 64, v146
	v_add_f32_e32 v140, v156, v140
	v_pk_mul_f32 v[158:159], v[136:137], v[136:137]
	v_cmp_lt_i32_e32 vcc, v143, v169
	v_add_f32_e32 v140, v157, v140
	v_add_f32_e32 v140, v158, v140
	v_cndmask_b32_e32 v143, v166, v143, vcc
	v_lshlrev_b32_e32 v146, 2, v143
	v_add_f32_e32 v140, v159, v140
	ds_bpermute_b32 v141, v146, v140
	v_xor_b32_e32 v149, 32, v166
	v_cmp_lt_i32_e32 vcc, v149, v169
	v_lshrrev_b32_e32 v167, 6, v151
	s_lshl_b32 s2, s58, 2
	v_cndmask_b32_e32 v144, v166, v149, vcc
	v_lshlrev_b32_e32 v149, 2, v144
	s_waitcnt lgkmcnt(0)
	v_add_f32_e32 v141, v140, v141
	ds_bpermute_b32 v156, v149, v141
	v_mov_b64_e32 v[160:161], s[24:25]
	v_and_or_b32 v140, v167, 3, s2
	v_mad_i64_i32 v[144:145], s[2:3], v139, s57, v[160:161]
	s_waitcnt lgkmcnt(0)
	v_add_f32_e32 v139, v141, v156
	v_fmamk_f32 v139, v139, 0x3c2aaaab, v1
	v_mul_f32_e32 v141, 0x4b800000, v139
	v_cmp_gt_f32_e32 vcc, s56, v139
	v_mul_lo_u32 v140, v140, s55
	v_mov_b32_e32 v143, v163
	v_cndmask_b32_e32 v139, v139, v141, vcc
	v_rsq_f32_e32 v139, v139
	v_ashrrev_i32_e32 v141, 31, v140
	v_lshl_add_u64 v[144:145], v[140:141], 1, v[144:145]
	v_lshl_add_u64 v[156:157], v[144:145], 0, v[142:143]
	v_mul_f32_e32 v143, 0x45800000, v139
	v_cndmask_b32_e32 v158, v139, v143, vcc
	v_mul_f32_e32 v126, v126, v158
	v_mul_f32_e32 v127, v127, v158
	v_mul_f32_e32 v128, v128, v158
	v_mul_f32_e32 v129, v129, v158
	v_mul_f32_e32 v122, v122, v158
	v_mul_f32_e32 v123, v123, v158
	v_mul_f32_e32 v124, v124, v158
	v_mul_f32_e32 v125, v125, v158
	v_mul_f32_e32 v118, v118, v158
	v_mul_f32_e32 v119, v119, v158
	v_mul_f32_e32 v120, v120, v158
	v_mul_f32_e32 v121, v121, v158
	v_mul_f32_e32 v114, v114, v158
	v_mul_f32_e32 v115, v115, v158
	v_mul_f32_e32 v116, v116, v158
	v_mul_f32_e32 v117, v117, v158
	s_cmp_eq_u32 s62, 1
	v_cmp_gt_u32_e64 s[4:5], 2, v150
	s_cselect_b64 s[30:31], -1, 0
	v_mul_f32_e32 v126, v170, v126
	v_mul_f32_e32 v127, v171, v127
	v_mul_f32_e32 v128, v172, v128
	v_mul_f32_e32 v129, v173, v129
	v_cvt_pk_bf16_f32 v126, v126, v127
	v_cvt_pk_bf16_f32 v127, v128, v129
	global_store_dwordx2 v[156:157], v[126:127], off
	s_cmp_lg_u32 s62, 1
	v_mul_f32_e32 v122, v174, v122
	v_mul_f32_e32 v123, v175, v123
	v_mul_f32_e32 v124, v176, v124
	v_mul_f32_e32 v125, v177, v125
	v_cvt_pk_bf16_f32 v122, v122, v123
	v_cvt_pk_bf16_f32 v123, v124, v125
	global_store_dwordx2 v[156:157], v[122:123], off offset:32
	v_mul_f32_e32 v118, v178, v118
	v_mul_f32_e32 v119, v179, v119
	v_mul_f32_e32 v120, v180, v120
	v_mul_f32_e32 v121, v121, v181
	v_cvt_pk_bf16_f32 v118, v118, v119
	v_cvt_pk_bf16_f32 v119, v120, v121
	global_store_dwordx2 v[156:157], v[118:119], off offset:64
	v_and_b32_e32 v122, 16, v151
	v_cmp_eq_u32_e64 s[2:3], 0, v122
	v_mul_f32_e32 v114, v114, v182
	v_mul_f32_e32 v115, v115, v183
	v_mul_f32_e32 v116, v116, v184
	v_mul_f32_e32 v117, v117, v185
	v_cvt_pk_bf16_f32 v114, v114, v115
	v_cvt_pk_bf16_f32 v115, v116, v117
	global_store_dwordx2 v[156:157], v[114:115], off offset:96
	s_nop 0
	v_mov_b32_e32 v114, v186
	v_mov_b32_e32 v115, v187
	v_mov_b32_e32 v116, v188
	v_mov_b32_e32 v117, v189
	v_pk_mul_f32 v[114:115], v[158:159], v[114:115] op_sel_hi:[0,1]
	v_pk_mul_f32 v[116:117], v[158:159], v[116:117] op_sel_hi:[0,1]
	v_pk_mul_f32 v[122:123], v[158:159], v[190:191] op_sel_hi:[0,1]
	v_pk_mul_f32 v[124:125], v[158:159], v[192:193] op_sel_hi:[0,1]
	v_pk_mul_f32 v[120:121], v[130:131], v[114:115]
	v_pk_mul_f32 v[118:119], v[132:133], v[116:117]
	v_pk_mul_f32 v[116:117], v[134:135], v[122:123]
	v_pk_mul_f32 v[114:115], v[136:137], v[124:125]
	s_cbranch_scc1 .LBB0_1869
	v_add_u32_e32 v122, s60, v147
	v_ashrrev_i32_e32 v123, 6, v122
	v_and_b32_e32 v122, 63, v122
	v_cndmask_b32_e64 v122, v122, v123, s[4:5]
	v_cvt_f32_i32_e32 v130, v122
	ds_bpermute_b32 v122, v146, v120
	ds_bpermute_b32 v123, v146, v121
	v_mul_f32_e32 v125, 0x3ea1e89b, v130
	v_mul_f32_e32 v126, 0.15915494, v130
	v_mul_f32_e32 v127, 0.15915494, v125
	v_sin_f32_e32 v124, v126
	v_sin_f32_e32 v125, v127
	v_mul_f32_e32 v129, 0x3d0186e3, v130
	v_mul_f32_e32 v132, 0.15915494, v129
	v_cos_f32_e32 v126, v126
	s_waitcnt lgkmcnt(0)
	v_pk_mul_f32 v[122:123], v[124:125], v[122:123]
	v_mul_f32_e32 v125, 0x3dcccccd, v130
	ds_bpermute_b32 v124, v146, v118
	v_mul_f32_e32 v131, 0.15915494, v125
	ds_bpermute_b32 v125, v146, v119
	v_cos_f32_e32 v127, v127
	v_sin_f32_e32 v128, v131
	v_sin_f32_e32 v129, v132
	v_cndmask_b32_e64 v123, v123, -v123, s[2:3]
	v_cndmask_b32_e64 v122, v122, -v122, s[2:3]
	v_pk_fma_f32 v[120:121], v[126:127], v[120:121], v[122:123]
	s_waitcnt lgkmcnt(0)
	v_pk_mul_f32 v[124:125], v[128:129], v[124:125]
	v_mul_f32_e32 v127, 0x3c23d70b, v130
	v_mul_f32_e32 v129, 0x3b4f3e39, v130
	v_cos_f32_e32 v122, v131
	v_cos_f32_e32 v123, v132
	ds_bpermute_b32 v126, v146, v116
	v_mul_f32_e32 v131, 0.15915494, v127
	ds_bpermute_b32 v127, v146, v117
	v_mul_f32_e32 v132, 0.15915494, v129
	v_sin_f32_e32 v128, v131
	v_sin_f32_e32 v129, v132
	v_cndmask_b32_e64 v125, v125, -v125, s[2:3]
	v_cndmask_b32_e64 v124, v124, -v124, s[2:3]
	v_pk_fma_f32 v[118:119], v[122:123], v[118:119], v[124:125]
	v_cos_f32_e32 v122, v131
	v_cos_f32_e32 v123, v132
	s_waitcnt lgkmcnt(0)
	v_pk_mul_f32 v[124:125], v[128:129], v[126:127]
	v_mul_f32_e32 v127, 0x3a831270, v130
	v_mul_f32_e32 v129, 0x39a5cb61, v130
	ds_bpermute_b32 v126, v146, v114
	v_mul_f32_e32 v131, 0.15915494, v127
	ds_bpermute_b32 v127, v146, v115
	v_mul_f32_e32 v130, 0.15915494, v129
	v_sin_f32_e32 v128, v131
	v_sin_f32_e32 v129, v130
	v_cndmask_b32_e64 v125, v125, -v125, s[2:3]
	v_cndmask_b32_e64 v124, v124, -v124, s[2:3]
	v_pk_fma_f32 v[116:117], v[122:123], v[116:117], v[124:125]
	v_cos_f32_e32 v122, v131
	v_cos_f32_e32 v123, v130
	s_waitcnt lgkmcnt(0)
	v_pk_mul_f32 v[124:125], v[128:129], v[126:127]
	s_nop 0
	v_cndmask_b32_e64 v125, v125, -v125, s[2:3]
	v_cndmask_b32_e64 v124, v124, -v124, s[2:3]
	v_pk_fma_f32 v[114:115], v[122:123], v[114:115], v[124:125]

.LBB0_1875:
	v_mul_f32_e32 v127, v111, v111
	v_fmac_f32_e32 v127, v110, v110
	v_fmac_f32_e32 v127, v112, v112
	v_fmac_f32_e32 v127, v113, v113
	v_fmac_f32_e32 v127, v106, v106
	v_fmac_f32_e32 v127, v107, v107
	v_fmac_f32_e32 v127, v108, v108
	v_fmac_f32_e32 v127, v109, v109
	v_fmac_f32_e32 v127, v102, v102
	v_fmac_f32_e32 v127, v103, v103
	v_fmac_f32_e32 v127, v104, v104
	v_fmac_f32_e32 v127, v105, v105
	v_fmac_f32_e32 v127, v98, v98
	v_fmac_f32_e32 v127, v99, v99
	v_fmac_f32_e32 v127, v100, v100
	s_waitcnt vmcnt(0)
	v_pk_mul_f32 v[136:137], v[114:115], v[114:115]
	v_fmac_f32_e32 v127, v101, v101
	v_add_f32_e32 v127, v127, v136
	v_pk_mul_f32 v[142:143], v[116:117], v[116:117]
	v_add_f32_e32 v127, v137, v127
	v_add_f32_e32 v127, v142, v127
	v_pk_mul_f32 v[144:145], v[118:119], v[118:119]
	v_add_f32_e32 v127, v143, v127
	v_add_f32_e32 v127, v144, v127
	v_pk_mul_f32 v[150:151], v[120:121], v[120:121]
	v_add_f32_e32 v127, v145, v127
	v_add_f32_e32 v127, v150, v127
	v_add_f32_e32 v127, v151, v127
	ds_bpermute_b32 v129, v146, v127
	v_mov_b64_e32 v[136:137], s[24:25]
	v_lshlrev_b32_e32 v126, 1, v126
	s_waitcnt lgkmcnt(0)
	v_add_f32_e32 v129, v127, v129
	ds_bpermute_b32 v131, v149, v129
	v_mov_b32_e32 v127, v163
	s_waitcnt lgkmcnt(0)
	v_add_f32_e32 v129, v129, v131
	v_fmamk_f32 v129, v129, 0x3c2aaaab, v1
	v_mul_f32_e32 v131, 0x4b800000, v129
	v_cmp_gt_f32_e32 vcc, s56, v129
	s_nop 1
	v_cndmask_b32_e32 v129, v129, v131, vcc
	v_rsq_f32_e32 v131, v129
	v_mad_i64_i32 v[128:129], s[6:7], v128, s57, v[136:137]
	v_lshl_add_u64 v[128:129], v[140:141], 1, v[128:129]
	v_lshl_add_u64 v[136:137], v[128:129], 0, v[126:127]
	v_mul_f32_e32 v127, 0x45800000, v131
	v_cndmask_b32_e32 v142, v131, v127, vcc
	v_mul_f32_e32 v110, v110, v142
	v_mul_f32_e32 v111, v111, v142
	v_mul_f32_e32 v112, v112, v142
	v_mul_f32_e32 v113, v113, v142
	v_mul_f32_e32 v106, v106, v142
	v_mul_f32_e32 v107, v107, v142
	v_mul_f32_e32 v108, v108, v142
	v_mul_f32_e32 v109, v109, v142
	v_mul_f32_e32 v102, v102, v142
	v_mul_f32_e32 v103, v103, v142
	v_mul_f32_e32 v104, v104, v142
	v_mul_f32_e32 v105, v105, v142
	v_mul_f32_e32 v98, v98, v142
	v_mul_f32_e32 v99, v99, v142
	v_mul_f32_e32 v100, v100, v142
	v_mul_f32_e32 v101, v101, v142
	s_andn2_b64 vcc, exec, s[30:31]
	v_mul_f32_e32 v110, v170, v110
	v_mul_f32_e32 v111, v171, v111
	v_mul_f32_e32 v112, v172, v112
	v_mul_f32_e32 v113, v173, v113
	v_cvt_pk_bf16_f32 v110, v110, v111
	v_cvt_pk_bf16_f32 v111, v112, v113
	global_store_dwordx2 v[136:137], v[110:111], off
	v_mul_f32_e32 v106, v174, v106
	v_mul_f32_e32 v107, v175, v107
	v_mul_f32_e32 v108, v176, v108
	v_mul_f32_e32 v109, v177, v109
	v_cvt_pk_bf16_f32 v106, v106, v107
	v_cvt_pk_bf16_f32 v107, v108, v109
	global_store_dwordx2 v[136:137], v[106:107], off offset:32
	v_mul_f32_e32 v102, v178, v102
	v_mul_f32_e32 v103, v179, v103
	v_mul_f32_e32 v104, v180, v104
	v_mul_f32_e32 v105, v105, v181
	v_cvt_pk_bf16_f32 v102, v102, v103
	v_cvt_pk_bf16_f32 v103, v104, v105
	global_store_dwordx2 v[136:137], v[102:103], off offset:64
	v_cndmask_b32_e64 v106, 0, 1, s[30:31]
	v_cmp_ne_u32_e64 s[6:7], 1, v106
	v_mul_f32_e32 v98, v98, v182
	v_mul_f32_e32 v99, v99, v183
	v_mul_f32_e32 v100, v100, v184
	v_mul_f32_e32 v101, v101, v185
	v_cvt_pk_bf16_f32 v98, v98, v99
	v_cvt_pk_bf16_f32 v99, v100, v101
	global_store_dwordx2 v[136:137], v[98:99], off offset:96
	s_nop 0
	v_mov_b32_e32 v98, v186
	v_mov_b32_e32 v99, v187
	v_mov_b32_e32 v100, v188
	v_mov_b32_e32 v101, v189
	v_pk_mul_f32 v[98:99], v[142:143], v[98:99] op_sel_hi:[0,1]
	v_pk_mul_f32 v[100:101], v[142:143], v[100:101] op_sel_hi:[0,1]
	v_pk_mul_f32 v[106:107], v[142:143], v[190:191] op_sel_hi:[0,1]
	v_pk_mul_f32 v[108:109], v[142:143], v[192:193] op_sel_hi:[0,1]
	v_pk_mul_f32 v[104:105], v[114:115], v[98:99]
	v_pk_mul_f32 v[102:103], v[116:117], v[100:101]
	v_pk_mul_f32 v[100:101], v[118:119], v[106:107]
	v_pk_mul_f32 v[98:99], v[120:121], v[108:109]
	s_cbranch_vccnz .LBB0_1877
	v_add_u32_e32 v106, s60, v130
	v_ashrrev_i32_e32 v107, 6, v106
	v_and_b32_e32 v106, 63, v106
	v_cndmask_b32_e64 v106, v106, v107, s[4:5]
	v_cvt_f32_i32_e32 v114, v106
	ds_bpermute_b32 v106, v146, v104
	ds_bpermute_b32 v107, v146, v105
	v_mul_f32_e32 v109, 0x3ea1e89b, v114
	v_mul_f32_e32 v110, 0.15915494, v114
	v_mul_f32_e32 v111, 0.15915494, v109
	v_sin_f32_e32 v108, v110
	v_sin_f32_e32 v109, v111
	v_mul_f32_e32 v113, 0x3d0186e3, v114
	v_mul_f32_e32 v116, 0.15915494, v113
	v_cos_f32_e32 v110, v110
	s_waitcnt lgkmcnt(0)
	v_pk_mul_f32 v[106:107], v[108:109], v[106:107]
	v_mul_f32_e32 v109, 0x3dcccccd, v114
	ds_bpermute_b32 v108, v146, v102
	v_mul_f32_e32 v115, 0.15915494, v109
	ds_bpermute_b32 v109, v146, v103
	v_cos_f32_e32 v111, v111
	v_sin_f32_e32 v112, v115
	v_sin_f32_e32 v113, v116
	v_cndmask_b32_e64 v107, v107, -v107, s[2:3]
	v_cndmask_b32_e64 v106, v106, -v106, s[2:3]
	v_pk_fma_f32 v[104:105], v[110:111], v[104:105], v[106:107]
	s_waitcnt lgkmcnt(0)
	v_pk_mul_f32 v[108:109], v[112:113], v[108:109]
	v_mul_f32_e32 v111, 0x3c23d70b, v114
	v_mul_f32_e32 v113, 0x3b4f3e39, v114
	v_cos_f32_e32 v106, v115
	v_cos_f32_e32 v107, v116
	ds_bpermute_b32 v110, v146, v100
	v_mul_f32_e32 v115, 0.15915494, v111
	ds_bpermute_b32 v111, v146, v101
	v_mul_f32_e32 v116, 0.15915494, v113
	v_sin_f32_e32 v112, v115
	v_sin_f32_e32 v113, v116
	v_cndmask_b32_e64 v109, v109, -v109, s[2:3]
	v_cndmask_b32_e64 v108, v108, -v108, s[2:3]
	v_pk_fma_f32 v[102:103], v[106:107], v[102:103], v[108:109]
	v_cos_f32_e32 v106, v115
	v_cos_f32_e32 v107, v116
	s_waitcnt lgkmcnt(0)
	v_pk_mul_f32 v[108:109], v[112:113], v[110:111]
	v_mul_f32_e32 v111, 0x3a831270, v114
	v_mul_f32_e32 v113, 0x39a5cb61, v114
	ds_bpermute_b32 v110, v146, v98
	v_mul_f32_e32 v115, 0.15915494, v111
	ds_bpermute_b32 v111, v146, v99
	v_mul_f32_e32 v114, 0.15915494, v113
	v_sin_f32_e32 v112, v115
	v_sin_f32_e32 v113, v114
	v_cndmask_b32_e64 v109, v109, -v109, s[2:3]
	v_cndmask_b32_e64 v108, v108, -v108, s[2:3]
	v_pk_fma_f32 v[100:101], v[106:107], v[100:101], v[108:109]
	v_cos_f32_e32 v106, v115
	v_cos_f32_e32 v107, v114
	s_waitcnt lgkmcnt(0)
	v_pk_mul_f32 v[108:109], v[112:113], v[110:111]
	s_nop 0
	v_cndmask_b32_e64 v109, v109, -v109, s[2:3]
	v_cndmask_b32_e64 v108, v108, -v108, s[2:3]
	v_pk_fma_f32 v[98:99], v[106:107], v[98:99], v[108:109]

.LBB0_1883:
	v_mul_f32_e32 v107, v95, v95
	v_fmac_f32_e32 v107, v94, v94
	v_fmac_f32_e32 v107, v96, v96
	v_fmac_f32_e32 v107, v97, v97
	v_fmac_f32_e32 v107, v90, v90
	v_fmac_f32_e32 v107, v91, v91
	v_fmac_f32_e32 v107, v92, v92
	v_fmac_f32_e32 v107, v93, v93
	v_fmac_f32_e32 v107, v86, v86
	v_fmac_f32_e32 v107, v87, v87
	v_fmac_f32_e32 v107, v88, v88
	v_fmac_f32_e32 v107, v89, v89
	v_fmac_f32_e32 v107, v82, v82
	v_fmac_f32_e32 v107, v83, v83
	v_fmac_f32_e32 v107, v84, v84
	s_waitcnt vmcnt(0)
	v_pk_mul_f32 v[114:115], v[98:99], v[98:99]
	v_fmac_f32_e32 v107, v85, v85
	v_add_f32_e32 v107, v107, v114
	v_pk_mul_f32 v[116:117], v[100:101], v[100:101]
	v_add_f32_e32 v107, v115, v107
	v_add_f32_e32 v107, v116, v107
	v_pk_mul_f32 v[118:119], v[102:103], v[102:103]
	v_add_f32_e32 v107, v117, v107
	v_add_f32_e32 v107, v118, v107
	v_pk_mul_f32 v[120:121], v[104:105], v[104:105]
	v_add_f32_e32 v107, v119, v107
	v_add_f32_e32 v107, v120, v107
	v_add_f32_e32 v107, v121, v107
	ds_bpermute_b32 v109, v146, v107
	v_mov_b64_e32 v[114:115], s[24:25]
	v_mov_b32_e32 v127, v163
	s_waitcnt lgkmcnt(0)
	v_add_f32_e32 v107, v107, v109
	ds_bpermute_b32 v109, v149, v107
	s_waitcnt lgkmcnt(0)
	v_add_f32_e32 v107, v107, v109
	v_fmamk_f32 v107, v107, 0x3c2aaaab, v1
	v_mul_f32_e32 v109, 0x4b800000, v107
	v_cmp_gt_f32_e32 vcc, s56, v107
	s_nop 1
	v_cndmask_b32_e32 v107, v107, v109, vcc
	v_rsq_f32_e32 v109, v107
	v_mad_i64_i32 v[106:107], s[30:31], v106, s57, v[114:115]
	v_lshl_add_u64 v[106:107], v[140:141], 1, v[106:107]
	v_mul_f32_e32 v116, 0x45800000, v109
	v_cndmask_b32_e32 v116, v109, v116, vcc
	v_mul_f32_e32 v94, v94, v116
	v_mul_f32_e32 v95, v95, v116
	v_lshl_add_u64 v[114:115], v[106:107], 0, v[126:127]
	v_mul_f32_e32 v96, v96, v116
	v_mul_f32_e32 v97, v97, v116
	v_mul_f32_e32 v90, v90, v116
	v_mul_f32_e32 v91, v91, v116
	v_mul_f32_e32 v92, v92, v116
	v_mul_f32_e32 v93, v93, v116
	v_mul_f32_e32 v86, v86, v116
	v_mul_f32_e32 v87, v87, v116
	v_mul_f32_e32 v88, v88, v116
	v_mul_f32_e32 v89, v89, v116
	v_mul_f32_e32 v82, v82, v116
	v_mul_f32_e32 v83, v83, v116
	v_mul_f32_e32 v84, v84, v116
	v_mul_f32_e32 v85, v85, v116
	s_and_b64 vcc, exec, s[6:7]
	v_mul_f32_e32 v94, v170, v94
	v_mul_f32_e32 v95, v171, v95
	v_mul_f32_e32 v96, v172, v96
	v_mul_f32_e32 v97, v173, v97
	v_cvt_pk_bf16_f32 v94, v94, v95
	v_cvt_pk_bf16_f32 v95, v96, v97
	global_store_dwordx2 v[114:115], v[94:95], off
	v_mul_f32_e32 v90, v174, v90
	v_mul_f32_e32 v91, v175, v91
	v_mul_f32_e32 v92, v176, v92
	v_mul_f32_e32 v93, v177, v93
	v_cvt_pk_bf16_f32 v90, v90, v91
	v_cvt_pk_bf16_f32 v91, v92, v93
	global_store_dwordx2 v[114:115], v[90:91], off offset:32
	v_mul_f32_e32 v86, v178, v86
	v_mul_f32_e32 v87, v179, v87
	v_mul_f32_e32 v88, v180, v88
	v_mul_f32_e32 v89, v89, v181
	v_cvt_pk_bf16_f32 v86, v86, v87
	v_cvt_pk_bf16_f32 v87, v88, v89
	global_store_dwordx2 v[114:115], v[86:87], off offset:64
	v_mul_f32_e32 v82, v82, v182
	v_mul_f32_e32 v83, v83, v183
	v_mul_f32_e32 v84, v84, v184
	v_mul_f32_e32 v85, v85, v185
	v_cvt_pk_bf16_f32 v82, v82, v83
	v_cvt_pk_bf16_f32 v83, v84, v85
	global_store_dwordx2 v[114:115], v[82:83], off offset:96
	s_nop 0
	v_mov_b32_e32 v82, v186
	v_mov_b32_e32 v83, v187
	v_mov_b32_e32 v84, v188
	v_mov_b32_e32 v85, v189
	v_pk_mul_f32 v[82:83], v[116:117], v[82:83] op_sel_hi:[0,1]
	v_pk_mul_f32 v[84:85], v[116:117], v[84:85] op_sel_hi:[0,1]
	v_pk_mul_f32 v[90:91], v[116:117], v[190:191] op_sel_hi:[0,1]
	v_pk_mul_f32 v[92:93], v[116:117], v[192:193] op_sel_hi:[0,1]
	v_pk_mul_f32 v[88:89], v[98:99], v[82:83]
	v_pk_mul_f32 v[86:87], v[100:101], v[84:85]
	v_pk_mul_f32 v[84:85], v[102:103], v[90:91]
	v_pk_mul_f32 v[82:83], v[104:105], v[92:93]
	s_cbranch_vccnz .LBB0_1885
	v_add_u32_e32 v90, s60, v108
	v_ashrrev_i32_e32 v91, 6, v90
	v_and_b32_e32 v90, 63, v90
	v_cndmask_b32_e64 v90, v90, v91, s[4:5]
	v_cvt_f32_i32_e32 v98, v90
	ds_bpermute_b32 v90, v146, v88
	ds_bpermute_b32 v91, v146, v89
	v_mul_f32_e32 v93, 0x3ea1e89b, v98
	v_mul_f32_e32 v94, 0.15915494, v98
	v_mul_f32_e32 v95, 0.15915494, v93
	v_sin_f32_e32 v92, v94
	v_sin_f32_e32 v93, v95
	v_mul_f32_e32 v97, 0x3d0186e3, v98
	v_mul_f32_e32 v100, 0.15915494, v97
	v_cos_f32_e32 v94, v94
	s_waitcnt lgkmcnt(0)
	v_pk_mul_f32 v[90:91], v[92:93], v[90:91]
	v_mul_f32_e32 v93, 0x3dcccccd, v98
	ds_bpermute_b32 v92, v146, v86
	v_mul_f32_e32 v99, 0.15915494, v93
	ds_bpermute_b32 v93, v146, v87
	v_cos_f32_e32 v95, v95
	v_sin_f32_e32 v96, v99
	v_sin_f32_e32 v97, v100
	v_cndmask_b32_e64 v91, v91, -v91, s[2:3]
	v_cndmask_b32_e64 v90, v90, -v90, s[2:3]
	v_pk_fma_f32 v[88:89], v[94:95], v[88:89], v[90:91]
	s_waitcnt lgkmcnt(0)
	v_pk_mul_f32 v[92:93], v[96:97], v[92:93]
	v_mul_f32_e32 v95, 0x3c23d70b, v98
	v_mul_f32_e32 v97, 0x3b4f3e39, v98
	v_cos_f32_e32 v90, v99
	v_cos_f32_e32 v91, v100
	ds_bpermute_b32 v94, v146, v84
	v_mul_f32_e32 v99, 0.15915494, v95
	ds_bpermute_b32 v95, v146, v85
	v_mul_f32_e32 v100, 0.15915494, v97
	v_sin_f32_e32 v96, v99
	v_sin_f32_e32 v97, v100
	v_cndmask_b32_e64 v93, v93, -v93, s[2:3]
	v_cndmask_b32_e64 v92, v92, -v92, s[2:3]
	v_pk_fma_f32 v[86:87], v[90:91], v[86:87], v[92:93]
	v_cos_f32_e32 v90, v99
	v_cos_f32_e32 v91, v100
	s_waitcnt lgkmcnt(0)
	v_pk_mul_f32 v[92:93], v[96:97], v[94:95]
	v_mul_f32_e32 v95, 0x3a831270, v98
	v_mul_f32_e32 v97, 0x39a5cb61, v98
	ds_bpermute_b32 v94, v146, v82
	v_mul_f32_e32 v99, 0.15915494, v95
	ds_bpermute_b32 v95, v146, v83
	v_mul_f32_e32 v98, 0.15915494, v97
	v_sin_f32_e32 v96, v99
	v_sin_f32_e32 v97, v98
	v_cndmask_b32_e64 v93, v93, -v93, s[2:3]
	v_cndmask_b32_e64 v92, v92, -v92, s[2:3]
	v_pk_fma_f32 v[84:85], v[90:91], v[84:85], v[92:93]
	v_cos_f32_e32 v90, v99
	v_cos_f32_e32 v91, v98
	s_waitcnt lgkmcnt(0)
	v_pk_mul_f32 v[92:93], v[96:97], v[94:95]
	s_nop 0
	v_cndmask_b32_e64 v93, v93, -v93, s[2:3]
	v_cndmask_b32_e64 v92, v92, -v92, s[2:3]
	v_pk_fma_f32 v[82:83], v[90:91], v[82:83], v[92:93]

.LBB0_1891:
	v_mul_f32_e32 v91, v79, v79
	v_fmac_f32_e32 v91, v78, v78
	v_fmac_f32_e32 v91, v80, v80
	v_fmac_f32_e32 v91, v81, v81
	v_fmac_f32_e32 v91, v74, v74
	v_fmac_f32_e32 v91, v75, v75
	v_fmac_f32_e32 v91, v76, v76
	v_fmac_f32_e32 v91, v77, v77
	v_fmac_f32_e32 v91, v70, v70
	v_fmac_f32_e32 v91, v71, v71
	v_fmac_f32_e32 v91, v72, v72
	v_fmac_f32_e32 v91, v73, v73
	v_fmac_f32_e32 v91, v66, v66
	v_fmac_f32_e32 v91, v67, v67
	v_fmac_f32_e32 v91, v68, v68
	s_waitcnt vmcnt(0)
	v_pk_mul_f32 v[98:99], v[82:83], v[82:83]
	v_fmac_f32_e32 v91, v69, v69
	v_add_f32_e32 v91, v91, v98
	v_pk_mul_f32 v[100:101], v[84:85], v[84:85]
	v_add_f32_e32 v91, v99, v91
	v_add_f32_e32 v91, v100, v91
	v_pk_mul_f32 v[102:103], v[86:87], v[86:87]
	v_add_f32_e32 v91, v101, v91
	v_add_f32_e32 v91, v102, v91
	v_pk_mul_f32 v[104:105], v[88:89], v[88:89]
	v_add_f32_e32 v91, v103, v91
	v_add_f32_e32 v91, v104, v91
	v_add_f32_e32 v91, v105, v91
	ds_bpermute_b32 v93, v146, v91
	v_mov_b64_e32 v[98:99], s[24:25]
	v_mov_b32_e32 v127, v163
	s_waitcnt lgkmcnt(0)
	v_add_f32_e32 v91, v91, v93
	ds_bpermute_b32 v93, v149, v91
	s_waitcnt lgkmcnt(0)
	v_add_f32_e32 v91, v91, v93
	v_fmamk_f32 v91, v91, 0x3c2aaaab, v1
	v_mul_f32_e32 v93, 0x4b800000, v91
	v_cmp_gt_f32_e32 vcc, s56, v91
	s_nop 1
	v_cndmask_b32_e32 v91, v91, v93, vcc
	v_rsq_f32_e32 v93, v91
	v_mad_i64_i32 v[90:91], s[30:31], v90, s57, v[98:99]
	v_lshl_add_u64 v[90:91], v[140:141], 1, v[90:91]
	v_mul_f32_e32 v100, 0x45800000, v93
	v_cndmask_b32_e32 v100, v93, v100, vcc
	v_mul_f32_e32 v78, v78, v100
	v_mul_f32_e32 v79, v79, v100
	v_lshl_add_u64 v[98:99], v[90:91], 0, v[126:127]
	v_mul_f32_e32 v80, v80, v100
	v_mul_f32_e32 v81, v81, v100
	v_mul_f32_e32 v74, v74, v100
	v_mul_f32_e32 v75, v75, v100
	v_mul_f32_e32 v76, v76, v100
	v_mul_f32_e32 v77, v77, v100
	v_mul_f32_e32 v70, v70, v100
	v_mul_f32_e32 v71, v71, v100
	v_mul_f32_e32 v72, v72, v100
	v_mul_f32_e32 v73, v73, v100
	v_mul_f32_e32 v66, v66, v100
	v_mul_f32_e32 v67, v67, v100
	v_mul_f32_e32 v68, v68, v100
	v_mul_f32_e32 v69, v69, v100
	s_and_b64 vcc, exec, s[6:7]
	v_mul_f32_e32 v78, v170, v78
	v_mul_f32_e32 v79, v171, v79
	v_mul_f32_e32 v80, v172, v80
	v_mul_f32_e32 v81, v173, v81
	v_cvt_pk_bf16_f32 v78, v78, v79
	v_cvt_pk_bf16_f32 v79, v80, v81
	global_store_dwordx2 v[98:99], v[78:79], off
	v_mul_f32_e32 v74, v174, v74
	v_mul_f32_e32 v75, v175, v75
	v_mul_f32_e32 v76, v176, v76
	v_mul_f32_e32 v77, v177, v77
	v_cvt_pk_bf16_f32 v74, v74, v75
	v_cvt_pk_bf16_f32 v75, v76, v77
	global_store_dwordx2 v[98:99], v[74:75], off offset:32
	v_mul_f32_e32 v70, v178, v70
	v_mul_f32_e32 v71, v179, v71
	v_mul_f32_e32 v72, v180, v72
	v_mul_f32_e32 v73, v73, v181
	v_cvt_pk_bf16_f32 v70, v70, v71
	v_cvt_pk_bf16_f32 v71, v72, v73
	global_store_dwordx2 v[98:99], v[70:71], off offset:64
	v_mul_f32_e32 v66, v66, v182
	v_mul_f32_e32 v67, v67, v183
	v_mul_f32_e32 v68, v68, v184
	v_mul_f32_e32 v69, v69, v185
	v_cvt_pk_bf16_f32 v66, v66, v67
	v_cvt_pk_bf16_f32 v67, v68, v69
	global_store_dwordx2 v[98:99], v[66:67], off offset:96
	s_nop 0
	v_mov_b32_e32 v66, v186
	v_mov_b32_e32 v67, v187
	v_mov_b32_e32 v68, v188
	v_mov_b32_e32 v69, v189
	v_pk_mul_f32 v[66:67], v[100:101], v[66:67] op_sel_hi:[0,1]
	v_pk_mul_f32 v[68:69], v[100:101], v[68:69] op_sel_hi:[0,1]
	v_pk_mul_f32 v[74:75], v[100:101], v[190:191] op_sel_hi:[0,1]
	v_pk_mul_f32 v[76:77], v[100:101], v[192:193] op_sel_hi:[0,1]
	v_pk_mul_f32 v[72:73], v[82:83], v[66:67]
	v_pk_mul_f32 v[70:71], v[84:85], v[68:69]
	v_pk_mul_f32 v[68:69], v[86:87], v[74:75]
	v_pk_mul_f32 v[66:67], v[88:89], v[76:77]
	s_cbranch_vccnz .LBB0_1893
	v_add_u32_e32 v74, s60, v92
	v_ashrrev_i32_e32 v75, 6, v74
	v_and_b32_e32 v74, 63, v74
	v_cndmask_b32_e64 v74, v74, v75, s[4:5]
	v_cvt_f32_i32_e32 v82, v74
	ds_bpermute_b32 v74, v146, v72
	ds_bpermute_b32 v75, v146, v73
	v_mul_f32_e32 v77, 0x3ea1e89b, v82
	v_mul_f32_e32 v78, 0.15915494, v82
	v_mul_f32_e32 v79, 0.15915494, v77
	v_sin_f32_e32 v76, v78
	v_sin_f32_e32 v77, v79
	v_mul_f32_e32 v81, 0x3d0186e3, v82
	v_mul_f32_e32 v84, 0.15915494, v81
	v_cos_f32_e32 v78, v78
	s_waitcnt lgkmcnt(0)
	v_pk_mul_f32 v[74:75], v[76:77], v[74:75]
	v_mul_f32_e32 v77, 0x3dcccccd, v82
	ds_bpermute_b32 v76, v146, v70
	v_mul_f32_e32 v83, 0.15915494, v77
	ds_bpermute_b32 v77, v146, v71
	v_cos_f32_e32 v79, v79
	v_sin_f32_e32 v80, v83
	v_sin_f32_e32 v81, v84
	v_cndmask_b32_e64 v75, v75, -v75, s[2:3]
	v_cndmask_b32_e64 v74, v74, -v74, s[2:3]
	v_pk_fma_f32 v[72:73], v[78:79], v[72:73], v[74:75]
	s_waitcnt lgkmcnt(0)
	v_pk_mul_f32 v[76:77], v[80:81], v[76:77]
	v_mul_f32_e32 v79, 0x3c23d70b, v82
	v_mul_f32_e32 v81, 0x3b4f3e39, v82
	v_cos_f32_e32 v74, v83
	v_cos_f32_e32 v75, v84
	ds_bpermute_b32 v78, v146, v68
	v_mul_f32_e32 v83, 0.15915494, v79
	ds_bpermute_b32 v79, v146, v69
	v_mul_f32_e32 v84, 0.15915494, v81
	v_sin_f32_e32 v80, v83
	v_sin_f32_e32 v81, v84
	v_cndmask_b32_e64 v77, v77, -v77, s[2:3]
	v_cndmask_b32_e64 v76, v76, -v76, s[2:3]
	v_pk_fma_f32 v[70:71], v[74:75], v[70:71], v[76:77]
	v_cos_f32_e32 v74, v83
	v_cos_f32_e32 v75, v84
	s_waitcnt lgkmcnt(0)
	v_pk_mul_f32 v[76:77], v[80:81], v[78:79]
	v_mul_f32_e32 v79, 0x3a831270, v82
	v_mul_f32_e32 v81, 0x39a5cb61, v82
	ds_bpermute_b32 v78, v146, v66
	v_mul_f32_e32 v83, 0.15915494, v79
	ds_bpermute_b32 v79, v146, v67
	v_mul_f32_e32 v82, 0.15915494, v81
	v_sin_f32_e32 v80, v83
	v_sin_f32_e32 v81, v82
	v_cndmask_b32_e64 v77, v77, -v77, s[2:3]
	v_cndmask_b32_e64 v76, v76, -v76, s[2:3]
	v_pk_fma_f32 v[68:69], v[74:75], v[68:69], v[76:77]
	v_cos_f32_e32 v74, v83
	v_cos_f32_e32 v75, v82
	s_waitcnt lgkmcnt(0)
	v_pk_mul_f32 v[76:77], v[80:81], v[78:79]
	s_nop 0
	v_cndmask_b32_e64 v77, v77, -v77, s[2:3]
	v_cndmask_b32_e64 v76, v76, -v76, s[2:3]
	v_pk_fma_f32 v[66:67], v[74:75], v[66:67], v[76:77]

.LBB0_1899:
	v_mul_f32_e32 v75, v63, v63
	v_fmac_f32_e32 v75, v62, v62
	v_fmac_f32_e32 v75, v64, v64
	v_fmac_f32_e32 v75, v65, v65
	v_fmac_f32_e32 v75, v58, v58
	v_fmac_f32_e32 v75, v59, v59
	v_fmac_f32_e32 v75, v60, v60
	v_fmac_f32_e32 v75, v61, v61
	v_fmac_f32_e32 v75, v54, v54
	v_fmac_f32_e32 v75, v55, v55
	v_fmac_f32_e32 v75, v56, v56
	v_fmac_f32_e32 v75, v57, v57
	v_fmac_f32_e32 v75, v50, v50
	v_fmac_f32_e32 v75, v51, v51
	v_fmac_f32_e32 v75, v52, v52
	s_waitcnt vmcnt(0)
	v_pk_mul_f32 v[82:83], v[66:67], v[66:67]
	v_fmac_f32_e32 v75, v53, v53
	v_add_f32_e32 v75, v75, v82
	v_pk_mul_f32 v[84:85], v[68:69], v[68:69]
	v_add_f32_e32 v75, v83, v75
	v_add_f32_e32 v75, v84, v75
	v_pk_mul_f32 v[86:87], v[70:71], v[70:71]
	v_add_f32_e32 v75, v85, v75
	v_add_f32_e32 v75, v86, v75
	v_pk_mul_f32 v[88:89], v[72:73], v[72:73]
	v_add_f32_e32 v75, v87, v75
	v_add_f32_e32 v75, v88, v75
	v_add_f32_e32 v75, v89, v75
	ds_bpermute_b32 v77, v146, v75
	v_mov_b64_e32 v[82:83], s[24:25]
	v_mov_b32_e32 v127, v163
	s_waitcnt lgkmcnt(0)
	v_add_f32_e32 v75, v75, v77
	ds_bpermute_b32 v77, v149, v75
	s_waitcnt lgkmcnt(0)
	v_add_f32_e32 v75, v75, v77
	v_fmamk_f32 v75, v75, 0x3c2aaaab, v1
	v_mul_f32_e32 v77, 0x4b800000, v75
	v_cmp_gt_f32_e32 vcc, s56, v75
	s_nop 1
	v_cndmask_b32_e32 v75, v75, v77, vcc
	v_rsq_f32_e32 v77, v75
	v_mad_i64_i32 v[74:75], s[30:31], v74, s57, v[82:83]
	v_lshl_add_u64 v[74:75], v[140:141], 1, v[74:75]
	v_mul_f32_e32 v84, 0x45800000, v77
	v_cndmask_b32_e32 v84, v77, v84, vcc
	v_mul_f32_e32 v62, v62, v84
	v_mul_f32_e32 v63, v63, v84
	v_lshl_add_u64 v[82:83], v[74:75], 0, v[126:127]
	v_mul_f32_e32 v64, v64, v84
	v_mul_f32_e32 v65, v65, v84
	v_mul_f32_e32 v58, v58, v84
	v_mul_f32_e32 v59, v59, v84
	v_mul_f32_e32 v60, v60, v84
	v_mul_f32_e32 v61, v61, v84
	v_mul_f32_e32 v54, v54, v84
	v_mul_f32_e32 v55, v55, v84
	v_mul_f32_e32 v56, v56, v84
	v_mul_f32_e32 v57, v57, v84
	v_mul_f32_e32 v50, v50, v84
	v_mul_f32_e32 v51, v51, v84
	v_mul_f32_e32 v52, v52, v84
	v_mul_f32_e32 v53, v53, v84
	s_and_b64 vcc, exec, s[6:7]
	v_mul_f32_e32 v62, v170, v62
	v_mul_f32_e32 v63, v171, v63
	v_mul_f32_e32 v64, v172, v64
	v_mul_f32_e32 v65, v173, v65
	v_cvt_pk_bf16_f32 v62, v62, v63
	v_cvt_pk_bf16_f32 v63, v64, v65
	global_store_dwordx2 v[82:83], v[62:63], off
	v_mul_f32_e32 v58, v174, v58
	v_mul_f32_e32 v59, v175, v59
	v_mul_f32_e32 v60, v176, v60
	v_mul_f32_e32 v61, v177, v61
	v_cvt_pk_bf16_f32 v58, v58, v59
	v_cvt_pk_bf16_f32 v59, v60, v61
	global_store_dwordx2 v[82:83], v[58:59], off offset:32
	v_mul_f32_e32 v54, v178, v54
	v_mul_f32_e32 v55, v179, v55
	v_mul_f32_e32 v56, v180, v56
	v_mul_f32_e32 v57, v57, v181
	v_cvt_pk_bf16_f32 v54, v54, v55
	v_cvt_pk_bf16_f32 v55, v56, v57
	global_store_dwordx2 v[82:83], v[54:55], off offset:64
	v_mul_f32_e32 v50, v50, v182
	v_mul_f32_e32 v51, v51, v183
	v_mul_f32_e32 v52, v52, v184
	v_mul_f32_e32 v53, v53, v185
	v_cvt_pk_bf16_f32 v50, v50, v51
	v_cvt_pk_bf16_f32 v51, v52, v53
	global_store_dwordx2 v[82:83], v[50:51], off offset:96
	s_nop 0
	v_mov_b32_e32 v50, v186
	v_mov_b32_e32 v51, v187
	v_mov_b32_e32 v52, v188
	v_mov_b32_e32 v53, v189
	v_pk_mul_f32 v[50:51], v[84:85], v[50:51] op_sel_hi:[0,1]
	v_pk_mul_f32 v[52:53], v[84:85], v[52:53] op_sel_hi:[0,1]
	v_pk_mul_f32 v[58:59], v[84:85], v[190:191] op_sel_hi:[0,1]
	v_pk_mul_f32 v[60:61], v[84:85], v[192:193] op_sel_hi:[0,1]
	v_pk_mul_f32 v[56:57], v[66:67], v[50:51]
	v_pk_mul_f32 v[54:55], v[68:69], v[52:53]
	v_pk_mul_f32 v[52:53], v[70:71], v[58:59]
	v_pk_mul_f32 v[50:51], v[72:73], v[60:61]
	s_cbranch_vccnz .LBB0_1901
	v_add_u32_e32 v58, s60, v76
	v_ashrrev_i32_e32 v59, 6, v58
	v_and_b32_e32 v58, 63, v58
	v_cndmask_b32_e64 v58, v58, v59, s[4:5]
	v_cvt_f32_i32_e32 v66, v58
	ds_bpermute_b32 v58, v146, v56
	ds_bpermute_b32 v59, v146, v57
	v_mul_f32_e32 v61, 0x3ea1e89b, v66
	v_mul_f32_e32 v62, 0.15915494, v66
	v_mul_f32_e32 v63, 0.15915494, v61
	v_sin_f32_e32 v60, v62
	v_sin_f32_e32 v61, v63
	v_mul_f32_e32 v65, 0x3d0186e3, v66
	v_mul_f32_e32 v68, 0.15915494, v65
	v_cos_f32_e32 v62, v62
	s_waitcnt lgkmcnt(0)
	v_pk_mul_f32 v[58:59], v[60:61], v[58:59]
	v_mul_f32_e32 v61, 0x3dcccccd, v66
	ds_bpermute_b32 v60, v146, v54
	v_mul_f32_e32 v67, 0.15915494, v61
	ds_bpermute_b32 v61, v146, v55
	v_cos_f32_e32 v63, v63
	v_sin_f32_e32 v64, v67
	v_sin_f32_e32 v65, v68
	v_cndmask_b32_e64 v59, v59, -v59, s[2:3]
	v_cndmask_b32_e64 v58, v58, -v58, s[2:3]
	v_pk_fma_f32 v[56:57], v[62:63], v[56:57], v[58:59]
	s_waitcnt lgkmcnt(0)
	v_pk_mul_f32 v[60:61], v[64:65], v[60:61]
	v_mul_f32_e32 v63, 0x3c23d70b, v66
	v_mul_f32_e32 v65, 0x3b4f3e39, v66
	v_cos_f32_e32 v58, v67
	v_cos_f32_e32 v59, v68
	ds_bpermute_b32 v62, v146, v52
	v_mul_f32_e32 v67, 0.15915494, v63
	ds_bpermute_b32 v63, v146, v53
	v_mul_f32_e32 v68, 0.15915494, v65
	v_sin_f32_e32 v64, v67
	v_sin_f32_e32 v65, v68
	v_cndmask_b32_e64 v61, v61, -v61, s[2:3]
	v_cndmask_b32_e64 v60, v60, -v60, s[2:3]
	v_pk_fma_f32 v[54:55], v[58:59], v[54:55], v[60:61]
	v_cos_f32_e32 v58, v67
	v_cos_f32_e32 v59, v68
	s_waitcnt lgkmcnt(0)
	v_pk_mul_f32 v[60:61], v[64:65], v[62:63]
	v_mul_f32_e32 v63, 0x3a831270, v66
	v_mul_f32_e32 v65, 0x39a5cb61, v66
	ds_bpermute_b32 v62, v146, v50
	v_mul_f32_e32 v67, 0.15915494, v63
	ds_bpermute_b32 v63, v146, v51
	v_mul_f32_e32 v66, 0.15915494, v65
	v_sin_f32_e32 v64, v67
	v_sin_f32_e32 v65, v66
	v_cndmask_b32_e64 v61, v61, -v61, s[2:3]
	v_cndmask_b32_e64 v60, v60, -v60, s[2:3]
	v_pk_fma_f32 v[52:53], v[58:59], v[52:53], v[60:61]
	v_cos_f32_e32 v58, v67
	v_cos_f32_e32 v59, v66
	s_waitcnt lgkmcnt(0)
	v_pk_mul_f32 v[60:61], v[64:65], v[62:63]
	s_nop 0
	v_cndmask_b32_e64 v61, v61, -v61, s[2:3]
	v_cndmask_b32_e64 v60, v60, -v60, s[2:3]
	v_pk_fma_f32 v[50:51], v[58:59], v[50:51], v[60:61]

.LBB0_1907:
	v_mul_f32_e32 v59, v47, v47
	v_fmac_f32_e32 v59, v46, v46
	v_fmac_f32_e32 v59, v48, v48
	v_fmac_f32_e32 v59, v49, v49
	v_fmac_f32_e32 v59, v42, v42
	v_fmac_f32_e32 v59, v43, v43
	v_fmac_f32_e32 v59, v44, v44
	v_fmac_f32_e32 v59, v45, v45
	v_fmac_f32_e32 v59, v38, v38
	v_fmac_f32_e32 v59, v39, v39
	v_fmac_f32_e32 v59, v40, v40
	v_fmac_f32_e32 v59, v41, v41
	v_fmac_f32_e32 v59, v34, v34
	v_fmac_f32_e32 v59, v35, v35
	v_fmac_f32_e32 v59, v36, v36
	s_waitcnt vmcnt(0)
	v_pk_mul_f32 v[66:67], v[50:51], v[50:51]
	v_fmac_f32_e32 v59, v37, v37
	v_add_f32_e32 v59, v59, v66
	v_pk_mul_f32 v[68:69], v[52:53], v[52:53]
	v_add_f32_e32 v59, v67, v59
	v_add_f32_e32 v59, v68, v59
	v_pk_mul_f32 v[70:71], v[54:55], v[54:55]
	v_add_f32_e32 v59, v69, v59
	v_add_f32_e32 v59, v70, v59
	v_pk_mul_f32 v[72:73], v[56:57], v[56:57]
	v_add_f32_e32 v59, v71, v59
	v_add_f32_e32 v59, v72, v59
	v_add_f32_e32 v59, v73, v59
	ds_bpermute_b32 v61, v146, v59
	v_mov_b64_e32 v[66:67], s[24:25]
	v_mov_b32_e32 v127, v163
	s_waitcnt lgkmcnt(0)
	v_add_f32_e32 v59, v59, v61
	ds_bpermute_b32 v61, v149, v59
	s_waitcnt lgkmcnt(0)
	v_add_f32_e32 v59, v59, v61
	v_fmamk_f32 v59, v59, 0x3c2aaaab, v1
	v_mul_f32_e32 v61, 0x4b800000, v59
	v_cmp_gt_f32_e32 vcc, s56, v59
	s_nop 1
	v_cndmask_b32_e32 v59, v59, v61, vcc
	v_rsq_f32_e32 v61, v59
	v_mad_i64_i32 v[58:59], s[30:31], v58, s57, v[66:67]
	v_lshl_add_u64 v[58:59], v[140:141], 1, v[58:59]
	v_mul_f32_e32 v68, 0x45800000, v61
	v_cndmask_b32_e32 v68, v61, v68, vcc
	v_mul_f32_e32 v46, v46, v68
	v_mul_f32_e32 v47, v47, v68
	v_lshl_add_u64 v[66:67], v[58:59], 0, v[126:127]
	v_mul_f32_e32 v48, v48, v68
	v_mul_f32_e32 v49, v49, v68
	v_mul_f32_e32 v42, v42, v68
	v_mul_f32_e32 v43, v43, v68
	v_mul_f32_e32 v44, v44, v68
	v_mul_f32_e32 v45, v45, v68
	v_mul_f32_e32 v38, v38, v68
	v_mul_f32_e32 v39, v39, v68
	v_mul_f32_e32 v40, v40, v68
	v_mul_f32_e32 v41, v41, v68
	v_mul_f32_e32 v34, v34, v68
	v_mul_f32_e32 v35, v35, v68
	v_mul_f32_e32 v36, v36, v68
	v_mul_f32_e32 v37, v37, v68
	s_and_b64 vcc, exec, s[6:7]
	v_mul_f32_e32 v46, v170, v46
	v_mul_f32_e32 v47, v171, v47
	v_mul_f32_e32 v48, v172, v48
	v_mul_f32_e32 v49, v173, v49
	v_cvt_pk_bf16_f32 v46, v46, v47
	v_cvt_pk_bf16_f32 v47, v48, v49
	global_store_dwordx2 v[66:67], v[46:47], off
	v_mul_f32_e32 v42, v174, v42
	v_mul_f32_e32 v43, v175, v43
	v_mul_f32_e32 v44, v176, v44
	v_mul_f32_e32 v45, v177, v45
	v_cvt_pk_bf16_f32 v42, v42, v43
	v_cvt_pk_bf16_f32 v43, v44, v45
	global_store_dwordx2 v[66:67], v[42:43], off offset:32
	v_mul_f32_e32 v38, v178, v38
	v_mul_f32_e32 v39, v179, v39
	v_mul_f32_e32 v40, v180, v40
	v_mul_f32_e32 v41, v41, v181
	v_cvt_pk_bf16_f32 v38, v38, v39
	v_cvt_pk_bf16_f32 v39, v40, v41
	global_store_dwordx2 v[66:67], v[38:39], off offset:64
	v_mul_f32_e32 v34, v34, v182
	v_mul_f32_e32 v35, v35, v183
	v_mul_f32_e32 v36, v36, v184
	v_mul_f32_e32 v37, v37, v185
	v_cvt_pk_bf16_f32 v34, v34, v35
	v_cvt_pk_bf16_f32 v35, v36, v37
	global_store_dwordx2 v[66:67], v[34:35], off offset:96
	s_nop 0
	v_mov_b32_e32 v34, v186
	v_mov_b32_e32 v35, v187
	v_mov_b32_e32 v36, v188
	v_mov_b32_e32 v37, v189
	v_pk_mul_f32 v[34:35], v[68:69], v[34:35] op_sel_hi:[0,1]
	v_pk_mul_f32 v[36:37], v[68:69], v[36:37] op_sel_hi:[0,1]
	v_pk_mul_f32 v[42:43], v[68:69], v[190:191] op_sel_hi:[0,1]
	v_pk_mul_f32 v[44:45], v[68:69], v[192:193] op_sel_hi:[0,1]
	v_pk_mul_f32 v[40:41], v[50:51], v[34:35]
	v_pk_mul_f32 v[38:39], v[52:53], v[36:37]
	v_pk_mul_f32 v[36:37], v[54:55], v[42:43]
	v_pk_mul_f32 v[34:35], v[56:57], v[44:45]
	s_cbranch_vccnz .LBB0_1909
	v_add_u32_e32 v42, s60, v60
	v_ashrrev_i32_e32 v43, 6, v42
	v_and_b32_e32 v42, 63, v42
	v_cndmask_b32_e64 v42, v42, v43, s[4:5]
	v_cvt_f32_i32_e32 v50, v42
	ds_bpermute_b32 v42, v146, v40
	ds_bpermute_b32 v43, v146, v41
	v_mul_f32_e32 v45, 0x3ea1e89b, v50
	v_mul_f32_e32 v46, 0.15915494, v50
	v_mul_f32_e32 v47, 0.15915494, v45
	v_sin_f32_e32 v44, v46
	v_sin_f32_e32 v45, v47
	v_mul_f32_e32 v49, 0x3d0186e3, v50
	v_mul_f32_e32 v52, 0.15915494, v49
	v_cos_f32_e32 v46, v46
	s_waitcnt lgkmcnt(0)
	v_pk_mul_f32 v[42:43], v[44:45], v[42:43]
	v_mul_f32_e32 v45, 0x3dcccccd, v50
	ds_bpermute_b32 v44, v146, v38
	v_mul_f32_e32 v51, 0.15915494, v45
	ds_bpermute_b32 v45, v146, v39
	v_cos_f32_e32 v47, v47
	v_sin_f32_e32 v48, v51
	v_sin_f32_e32 v49, v52
	v_cndmask_b32_e64 v43, v43, -v43, s[2:3]
	v_cndmask_b32_e64 v42, v42, -v42, s[2:3]
	v_pk_fma_f32 v[40:41], v[46:47], v[40:41], v[42:43]
	s_waitcnt lgkmcnt(0)
	v_pk_mul_f32 v[44:45], v[48:49], v[44:45]
	v_mul_f32_e32 v47, 0x3c23d70b, v50
	v_mul_f32_e32 v49, 0x3b4f3e39, v50
	v_cos_f32_e32 v42, v51
	v_cos_f32_e32 v43, v52
	ds_bpermute_b32 v46, v146, v36
	v_mul_f32_e32 v51, 0.15915494, v47
	ds_bpermute_b32 v47, v146, v37
	v_mul_f32_e32 v52, 0.15915494, v49
	v_sin_f32_e32 v48, v51
	v_sin_f32_e32 v49, v52
	v_cndmask_b32_e64 v45, v45, -v45, s[2:3]
	v_cndmask_b32_e64 v44, v44, -v44, s[2:3]
	v_pk_fma_f32 v[38:39], v[42:43], v[38:39], v[44:45]
	v_cos_f32_e32 v42, v51
	v_cos_f32_e32 v43, v52
	s_waitcnt lgkmcnt(0)
	v_pk_mul_f32 v[44:45], v[48:49], v[46:47]
	v_mul_f32_e32 v47, 0x3a831270, v50
	v_mul_f32_e32 v49, 0x39a5cb61, v50
	ds_bpermute_b32 v46, v146, v34
	v_mul_f32_e32 v51, 0.15915494, v47
	ds_bpermute_b32 v47, v146, v35
	v_mul_f32_e32 v50, 0.15915494, v49
	v_sin_f32_e32 v48, v51
	v_sin_f32_e32 v49, v50
	v_cndmask_b32_e64 v45, v45, -v45, s[2:3]
	v_cndmask_b32_e64 v44, v44, -v44, s[2:3]
	v_pk_fma_f32 v[36:37], v[42:43], v[36:37], v[44:45]
	v_cos_f32_e32 v42, v51
	v_cos_f32_e32 v43, v50
	s_waitcnt lgkmcnt(0)
	v_pk_mul_f32 v[44:45], v[48:49], v[46:47]
	s_nop 0
	v_cndmask_b32_e64 v45, v45, -v45, s[2:3]
	v_cndmask_b32_e64 v44, v44, -v44, s[2:3]
	v_pk_fma_f32 v[34:35], v[42:43], v[34:35], v[44:45]

.LBB0_1915:
	v_mul_f32_e32 v43, v31, v31
	v_fmac_f32_e32 v43, v30, v30
	v_fmac_f32_e32 v43, v32, v32
	v_fmac_f32_e32 v43, v33, v33
	v_fmac_f32_e32 v43, v26, v26
	v_fmac_f32_e32 v43, v27, v27
	v_fmac_f32_e32 v43, v28, v28
	v_fmac_f32_e32 v43, v29, v29
	v_fmac_f32_e32 v43, v22, v22
	v_fmac_f32_e32 v43, v23, v23
	v_fmac_f32_e32 v43, v24, v24
	v_fmac_f32_e32 v43, v25, v25
	v_fmac_f32_e32 v43, v18, v18
	v_fmac_f32_e32 v43, v19, v19
	v_fmac_f32_e32 v43, v20, v20
	s_waitcnt vmcnt(0)
	v_pk_mul_f32 v[50:51], v[34:35], v[34:35]
	v_fmac_f32_e32 v43, v21, v21
	v_add_f32_e32 v43, v43, v50
	v_pk_mul_f32 v[52:53], v[36:37], v[36:37]
	v_add_f32_e32 v43, v51, v43
	v_add_f32_e32 v43, v52, v43
	v_pk_mul_f32 v[54:55], v[38:39], v[38:39]
	v_add_f32_e32 v43, v53, v43
	v_add_f32_e32 v43, v54, v43
	v_pk_mul_f32 v[56:57], v[40:41], v[40:41]
	v_add_f32_e32 v43, v55, v43
	v_add_f32_e32 v43, v56, v43
	v_add_f32_e32 v43, v57, v43
	ds_bpermute_b32 v45, v146, v43
	v_mov_b64_e32 v[50:51], s[24:25]
	v_mov_b32_e32 v127, v163
	s_waitcnt lgkmcnt(0)
	v_add_f32_e32 v43, v43, v45
	ds_bpermute_b32 v45, v149, v43
	s_waitcnt lgkmcnt(0)
	v_add_f32_e32 v43, v43, v45
	v_fmamk_f32 v43, v43, 0x3c2aaaab, v1
	v_mul_f32_e32 v45, 0x4b800000, v43
	v_cmp_gt_f32_e32 vcc, s56, v43
	s_nop 1
	v_cndmask_b32_e32 v43, v43, v45, vcc
	v_rsq_f32_e32 v45, v43
	v_mad_i64_i32 v[42:43], s[30:31], v42, s57, v[50:51]
	v_lshl_add_u64 v[42:43], v[140:141], 1, v[42:43]
	v_mul_f32_e32 v52, 0x45800000, v45
	v_cndmask_b32_e32 v52, v45, v52, vcc
	v_mul_f32_e32 v30, v30, v52
	v_mul_f32_e32 v31, v31, v52
	v_lshl_add_u64 v[50:51], v[42:43], 0, v[126:127]
	v_mul_f32_e32 v32, v32, v52
	v_mul_f32_e32 v33, v33, v52
	v_mul_f32_e32 v26, v26, v52
	v_mul_f32_e32 v27, v27, v52
	v_mul_f32_e32 v28, v28, v52
	v_mul_f32_e32 v29, v29, v52
	v_mul_f32_e32 v22, v22, v52
	v_mul_f32_e32 v23, v23, v52
	v_mul_f32_e32 v24, v24, v52
	v_mul_f32_e32 v25, v25, v52
	v_mul_f32_e32 v18, v18, v52
	v_mul_f32_e32 v19, v19, v52
	v_mul_f32_e32 v20, v20, v52
	v_mul_f32_e32 v21, v21, v52
	s_and_b64 vcc, exec, s[6:7]
	v_mul_f32_e32 v30, v170, v30
	v_mul_f32_e32 v31, v171, v31
	v_mul_f32_e32 v32, v172, v32
	v_mul_f32_e32 v33, v173, v33
	v_cvt_pk_bf16_f32 v30, v30, v31
	v_cvt_pk_bf16_f32 v31, v32, v33
	global_store_dwordx2 v[50:51], v[30:31], off
	v_mul_f32_e32 v26, v174, v26
	v_mul_f32_e32 v27, v175, v27
	v_mul_f32_e32 v28, v176, v28
	v_mul_f32_e32 v29, v177, v29
	v_cvt_pk_bf16_f32 v26, v26, v27
	v_cvt_pk_bf16_f32 v27, v28, v29
	global_store_dwordx2 v[50:51], v[26:27], off offset:32
	v_mul_f32_e32 v22, v178, v22
	v_mul_f32_e32 v23, v179, v23
	v_mul_f32_e32 v24, v180, v24
	v_mul_f32_e32 v25, v25, v181
	v_cvt_pk_bf16_f32 v22, v22, v23
	v_cvt_pk_bf16_f32 v23, v24, v25
	global_store_dwordx2 v[50:51], v[22:23], off offset:64
	v_mul_f32_e32 v18, v18, v182
	v_mul_f32_e32 v19, v19, v183
	v_mul_f32_e32 v20, v20, v184
	v_mul_f32_e32 v21, v21, v185
	v_cvt_pk_bf16_f32 v18, v18, v19
	v_cvt_pk_bf16_f32 v19, v20, v21
	global_store_dwordx2 v[50:51], v[18:19], off offset:96
	s_nop 0
	v_mov_b32_e32 v18, v186
	v_mov_b32_e32 v19, v187
	v_mov_b32_e32 v20, v188
	v_mov_b32_e32 v21, v189
	v_pk_mul_f32 v[18:19], v[52:53], v[18:19] op_sel_hi:[0,1]
	v_pk_mul_f32 v[20:21], v[52:53], v[20:21] op_sel_hi:[0,1]
	v_pk_mul_f32 v[26:27], v[52:53], v[190:191] op_sel_hi:[0,1]
	v_pk_mul_f32 v[28:29], v[52:53], v[192:193] op_sel_hi:[0,1]
	v_pk_mul_f32 v[24:25], v[34:35], v[18:19]
	v_pk_mul_f32 v[22:23], v[36:37], v[20:21]
	v_pk_mul_f32 v[20:21], v[38:39], v[26:27]
	v_pk_mul_f32 v[18:19], v[40:41], v[28:29]
	s_cbranch_vccnz .LBB0_1917
	v_add_u32_e32 v26, s60, v44
	v_ashrrev_i32_e32 v27, 6, v26
	v_and_b32_e32 v26, 63, v26
	v_cndmask_b32_e64 v26, v26, v27, s[4:5]
	v_cvt_f32_i32_e32 v34, v26
	ds_bpermute_b32 v26, v146, v24
	ds_bpermute_b32 v27, v146, v25
	v_mul_f32_e32 v29, 0x3ea1e89b, v34
	v_mul_f32_e32 v30, 0.15915494, v34
	v_mul_f32_e32 v31, 0.15915494, v29
	v_sin_f32_e32 v28, v30
	v_sin_f32_e32 v29, v31
	v_mul_f32_e32 v33, 0x3d0186e3, v34
	v_mul_f32_e32 v36, 0.15915494, v33
	v_cos_f32_e32 v30, v30
	s_waitcnt lgkmcnt(0)
	v_pk_mul_f32 v[26:27], v[28:29], v[26:27]
	v_mul_f32_e32 v29, 0x3dcccccd, v34
	ds_bpermute_b32 v28, v146, v22
	v_mul_f32_e32 v35, 0.15915494, v29
	ds_bpermute_b32 v29, v146, v23
	v_cos_f32_e32 v31, v31
	v_sin_f32_e32 v32, v35
	v_sin_f32_e32 v33, v36
	v_cndmask_b32_e64 v27, v27, -v27, s[2:3]
	v_cndmask_b32_e64 v26, v26, -v26, s[2:3]
	v_pk_fma_f32 v[24:25], v[30:31], v[24:25], v[26:27]
	s_waitcnt lgkmcnt(0)
	v_pk_mul_f32 v[28:29], v[32:33], v[28:29]
	v_mul_f32_e32 v31, 0x3c23d70b, v34
	v_mul_f32_e32 v33, 0x3b4f3e39, v34
	v_cos_f32_e32 v26, v35
	v_cos_f32_e32 v27, v36
	ds_bpermute_b32 v30, v146, v20
	v_mul_f32_e32 v35, 0.15915494, v31
	ds_bpermute_b32 v31, v146, v21
	v_mul_f32_e32 v36, 0.15915494, v33
	v_sin_f32_e32 v32, v35
	v_sin_f32_e32 v33, v36
	v_cndmask_b32_e64 v29, v29, -v29, s[2:3]
	v_cndmask_b32_e64 v28, v28, -v28, s[2:3]
	v_pk_fma_f32 v[22:23], v[26:27], v[22:23], v[28:29]
	v_cos_f32_e32 v26, v35
	v_cos_f32_e32 v27, v36
	s_waitcnt lgkmcnt(0)
	v_pk_mul_f32 v[28:29], v[32:33], v[30:31]
	v_mul_f32_e32 v31, 0x3a831270, v34
	v_mul_f32_e32 v33, 0x39a5cb61, v34
	ds_bpermute_b32 v30, v146, v18
	v_mul_f32_e32 v35, 0.15915494, v31
	ds_bpermute_b32 v31, v146, v19
	v_mul_f32_e32 v34, 0.15915494, v33
	v_sin_f32_e32 v32, v35
	v_sin_f32_e32 v33, v34
	v_cndmask_b32_e64 v29, v29, -v29, s[2:3]
	v_cndmask_b32_e64 v28, v28, -v28, s[2:3]
	v_pk_fma_f32 v[20:21], v[26:27], v[20:21], v[28:29]
	v_cos_f32_e32 v26, v35
	v_cos_f32_e32 v27, v34
	s_waitcnt lgkmcnt(0)
	v_pk_mul_f32 v[28:29], v[32:33], v[30:31]
	s_nop 0
	v_cndmask_b32_e64 v29, v29, -v29, s[2:3]
	v_cndmask_b32_e64 v28, v28, -v28, s[2:3]
	v_pk_fma_f32 v[18:19], v[26:27], v[18:19], v[28:29]

.LBB0_1923:
	v_mul_f32_e32 v27, v15, v15
	v_fmac_f32_e32 v27, v14, v14
	v_fmac_f32_e32 v27, v16, v16
	v_fmac_f32_e32 v27, v17, v17
	v_fmac_f32_e32 v27, v10, v10
	v_fmac_f32_e32 v27, v11, v11
	v_fmac_f32_e32 v27, v12, v12
	v_fmac_f32_e32 v27, v13, v13
	v_fmac_f32_e32 v27, v6, v6
	v_fmac_f32_e32 v27, v7, v7
	v_fmac_f32_e32 v27, v8, v8
	v_fmac_f32_e32 v27, v9, v9
	v_fmac_f32_e32 v27, v2, v2
	v_fmac_f32_e32 v27, v3, v3
	v_fmac_f32_e32 v27, v4, v4
	s_waitcnt vmcnt(0)
	v_pk_mul_f32 v[34:35], v[18:19], v[18:19]
	v_fmac_f32_e32 v27, v5, v5
	v_add_f32_e32 v27, v27, v34
	v_pk_mul_f32 v[36:37], v[20:21], v[20:21]
	v_add_f32_e32 v27, v35, v27
	v_add_f32_e32 v27, v36, v27
	v_pk_mul_f32 v[38:39], v[22:23], v[22:23]
	v_add_f32_e32 v27, v37, v27
	v_add_f32_e32 v27, v38, v27
	v_pk_mul_f32 v[40:41], v[24:25], v[24:25]
	v_add_f32_e32 v27, v39, v27
	v_add_f32_e32 v27, v40, v27
	v_add_f32_e32 v27, v41, v27
	ds_bpermute_b32 v29, v146, v27
	v_mov_b64_e32 v[34:35], s[24:25]
	v_mov_b32_e32 v127, v163
	s_waitcnt lgkmcnt(0)
	v_add_f32_e32 v27, v27, v29
	ds_bpermute_b32 v29, v149, v27
	s_waitcnt lgkmcnt(0)
	v_add_f32_e32 v27, v27, v29
	v_fmamk_f32 v27, v27, 0x3c2aaaab, v1
	v_mul_f32_e32 v29, 0x4b800000, v27
	v_cmp_gt_f32_e32 vcc, s56, v27
	s_nop 1
	v_cndmask_b32_e32 v27, v27, v29, vcc
	v_rsq_f32_e32 v29, v27
	v_mad_i64_i32 v[26:27], s[30:31], v26, s57, v[34:35]
	v_lshl_add_u64 v[26:27], v[140:141], 1, v[26:27]
	v_mul_f32_e32 v36, 0x45800000, v29
	v_cndmask_b32_e32 v36, v29, v36, vcc
	v_mul_f32_e32 v14, v14, v36
	v_mul_f32_e32 v15, v15, v36
	v_lshl_add_u64 v[34:35], v[26:27], 0, v[126:127]
	v_mul_f32_e32 v16, v16, v36
	v_mul_f32_e32 v17, v17, v36
	v_mul_f32_e32 v10, v10, v36
	v_mul_f32_e32 v11, v11, v36
	v_mul_f32_e32 v12, v12, v36
	v_mul_f32_e32 v13, v13, v36
	v_mul_f32_e32 v6, v6, v36
	v_mul_f32_e32 v7, v7, v36
	v_mul_f32_e32 v8, v8, v36
	v_mul_f32_e32 v9, v9, v36
	v_mul_f32_e32 v2, v2, v36
	v_mul_f32_e32 v3, v3, v36
	v_mul_f32_e32 v4, v4, v36
	v_mul_f32_e32 v5, v5, v36
	s_and_b64 vcc, exec, s[6:7]
	v_mul_f32_e32 v14, v170, v14
	v_mul_f32_e32 v15, v171, v15
	v_mul_f32_e32 v16, v172, v16
	v_mul_f32_e32 v17, v173, v17
	v_cvt_pk_bf16_f32 v14, v14, v15
	v_cvt_pk_bf16_f32 v15, v16, v17
	global_store_dwordx2 v[34:35], v[14:15], off
	v_mul_f32_e32 v10, v174, v10
	v_mul_f32_e32 v11, v175, v11
	v_mul_f32_e32 v12, v176, v12
	v_mul_f32_e32 v13, v177, v13
	v_cvt_pk_bf16_f32 v10, v10, v11
	v_cvt_pk_bf16_f32 v11, v12, v13
	global_store_dwordx2 v[34:35], v[10:11], off offset:32
	v_mul_f32_e32 v6, v178, v6
	v_mul_f32_e32 v7, v179, v7
	v_mul_f32_e32 v8, v180, v8
	v_mul_f32_e32 v9, v9, v181
	v_cvt_pk_bf16_f32 v6, v6, v7
	v_cvt_pk_bf16_f32 v7, v8, v9
	global_store_dwordx2 v[34:35], v[6:7], off offset:64
	v_mul_f32_e32 v2, v2, v182
	v_mul_f32_e32 v3, v3, v183
	v_mul_f32_e32 v4, v4, v184
	v_mul_f32_e32 v5, v5, v185
	v_cvt_pk_bf16_f32 v2, v2, v3
	v_cvt_pk_bf16_f32 v3, v4, v5
	global_store_dwordx2 v[34:35], v[2:3], off offset:96
	s_nop 0
	v_mov_b32_e32 v2, v186
	v_mov_b32_e32 v3, v187
	v_mov_b32_e32 v4, v188
	v_mov_b32_e32 v5, v189
	v_pk_mul_f32 v[2:3], v[36:37], v[2:3] op_sel_hi:[0,1]
	v_pk_mul_f32 v[4:5], v[36:37], v[4:5] op_sel_hi:[0,1]
	v_pk_mul_f32 v[10:11], v[36:37], v[190:191] op_sel_hi:[0,1]
	v_pk_mul_f32 v[12:13], v[36:37], v[192:193] op_sel_hi:[0,1]
	v_pk_mul_f32 v[8:9], v[18:19], v[2:3]
	v_pk_mul_f32 v[6:7], v[20:21], v[4:5]
	v_pk_mul_f32 v[4:5], v[22:23], v[10:11]
	v_pk_mul_f32 v[2:3], v[24:25], v[12:13]
	s_cbranch_vccnz .LBB0_1925
	v_add_u32_e32 v10, s60, v28
	v_ashrrev_i32_e32 v11, 6, v10
	v_and_b32_e32 v10, 63, v10
	v_cndmask_b32_e64 v10, v10, v11, s[4:5]
	v_cvt_f32_i32_e32 v18, v10
	ds_bpermute_b32 v10, v146, v8
	ds_bpermute_b32 v11, v146, v9
	v_mul_f32_e32 v13, 0x3ea1e89b, v18
	v_mul_f32_e32 v14, 0.15915494, v18
	v_mul_f32_e32 v15, 0.15915494, v13
	v_sin_f32_e32 v12, v14
	v_sin_f32_e32 v13, v15
	v_mul_f32_e32 v17, 0x3d0186e3, v18
	v_mul_f32_e32 v20, 0.15915494, v17
	v_cos_f32_e32 v14, v14
	s_waitcnt lgkmcnt(0)
	v_pk_mul_f32 v[10:11], v[12:13], v[10:11]
	v_mul_f32_e32 v13, 0x3dcccccd, v18
	ds_bpermute_b32 v12, v146, v6
	v_mul_f32_e32 v19, 0.15915494, v13
	ds_bpermute_b32 v13, v146, v7
	v_cos_f32_e32 v15, v15
	v_sin_f32_e32 v16, v19
	v_sin_f32_e32 v17, v20
	v_cndmask_b32_e64 v11, v11, -v11, s[2:3]
	v_cndmask_b32_e64 v10, v10, -v10, s[2:3]
	v_pk_fma_f32 v[8:9], v[14:15], v[8:9], v[10:11]
	s_waitcnt lgkmcnt(0)
	v_pk_mul_f32 v[12:13], v[16:17], v[12:13]
	v_mul_f32_e32 v15, 0x3c23d70b, v18
	v_mul_f32_e32 v17, 0x3b4f3e39, v18
	v_cos_f32_e32 v10, v19
	v_cos_f32_e32 v11, v20
	ds_bpermute_b32 v14, v146, v4
	v_mul_f32_e32 v19, 0.15915494, v15
	ds_bpermute_b32 v15, v146, v5
	v_mul_f32_e32 v20, 0.15915494, v17
	v_sin_f32_e32 v16, v19
	v_sin_f32_e32 v17, v20
	v_cndmask_b32_e64 v13, v13, -v13, s[2:3]
	v_cndmask_b32_e64 v12, v12, -v12, s[2:3]
	v_pk_fma_f32 v[6:7], v[10:11], v[6:7], v[12:13]
	v_cos_f32_e32 v10, v19
	v_cos_f32_e32 v11, v20
	s_waitcnt lgkmcnt(0)
	v_pk_mul_f32 v[12:13], v[16:17], v[14:15]
	v_mul_f32_e32 v15, 0x3a831270, v18
	v_mul_f32_e32 v17, 0x39a5cb61, v18
	ds_bpermute_b32 v14, v146, v2
	v_mul_f32_e32 v19, 0.15915494, v15
	ds_bpermute_b32 v15, v146, v3
	v_mul_f32_e32 v18, 0.15915494, v17
	v_sin_f32_e32 v16, v19
	v_sin_f32_e32 v17, v18
	v_cndmask_b32_e64 v13, v13, -v13, s[2:3]
	v_cndmask_b32_e64 v12, v12, -v12, s[2:3]
	v_pk_fma_f32 v[4:5], v[10:11], v[4:5], v[12:13]
	v_cos_f32_e32 v10, v19
	v_cos_f32_e32 v11, v18
	s_waitcnt lgkmcnt(0)
	v_pk_mul_f32 v[12:13], v[16:17], v[14:15]
	s_nop 0
	v_cndmask_b32_e64 v13, v13, -v13, s[2:3]
	v_cndmask_b32_e64 v12, v12, -v12, s[2:3]
	v_pk_fma_f32 v[2:3], v[10:11], v[2:3], v[12:13]
